# baseline (speedup 1.0000x reference)
; #define PG8_STAGE(bufoff, gbase, voff) do { _Pragma("unroll") for (int _i = 0; _i < 2; ++_i) \
;         __builtin_amdgcn_global_load_lds((const unsigned*)((const char*)(gbase) + (voff)[_i]), (PG8_LAS unsigned*)(lds + (bufoff) + ldsw + _i * 8192), 16, 0, 0); } while (0)
; #define PG8_LDA(dst, b, h) do { _Pragma("unroll") for (int m = 0; m < 4; ++m) _Pragma("unroll") for (int k = 0; k < 2; ++k) dst[m][k] = *(const PG8_LAS bf16x8*)(lds + PG8_SA(b, h) + aoff + m * 2048 + k * 1024); } while (0)
; #define PG8_LDB(dst, b, h) do { _Pragma("unroll") for (int n = 0; n < 2; ++n) _Pragma("unroll") for (int k = 0; k < 2; ++k) dst[n][k] = *(const PG8_LAS bf16x8*)(lds + PG8_SB(b, h) + boff + n * 2048 + k * 1024); } while (0)
; #define PG8_MMA(ai, bj, At, Bt) do { __builtin_amdgcn_s_setprio(1); _Pragma("unroll") for (int m = 0; m < 4; ++m) _Pragma("unroll") for (int n = 0; n < 2; ++n) _Pragma("unroll") for (int k = 0; k < 2; ++k) \
;         acc[ai][bj][m][n] = __builtin_amdgcn_mfma_f32_16x16x32_bf16(Bt[n][k], At[m][k], acc[ai][bj][m][n], 0, 0, 0); __builtin_amdgcn_s_setprio(0); } while (0)
; #define PG8_WAIT_V(n) asm volatile("s_waitcnt vmcnt(" #n ")" ::: "memory")
; #define PG8_WAIT_L(n) asm volatile("s_waitcnt lgkmcnt(" #n ")" ::: "memory")
; #define PG8_BAR __builtin_amdgcn_s_barrier()
; #define PG8_SCHED __builtin_amdgcn_sched_barrier(0)
; template <class Epi, class Sched, bool ALIGN_EPI = false, bool SP2 = false>
; __device__ __forceinline__ void gemm_phase(PG8_LAS unsigned char* lds, const Gemm g, const Sched& S, const Epi& E, const int wv) {
;     ...
;             const bool last = (t == nt - 2);
;             const char* a1 = cA + (size_t)(t + 1) * kstep;
;             const char* a2 = last ? nA : cA + (size_t)(t + 2) * kstep; const char* b2 = last ? nB : cB + (size_t)(t + 2) * kstep;
;             const char* a3 = a2 + kstep; const char* b3 = b2 + kstep;
;             if (last && has_next) S.a_ready(nxt);
;             if constexpr (SP2) {
;             PG8_LDB(B0, 0, 0); PG8_LDB(B1, 0, 1); PG8_SCHED; PG8_LDA(At, 0, 0); PG8_STAGE(PG8_SA(1, 1), a1 + hstep, voffA);
;             PG8_WAIT_V(8); PG8_WAIT_L(0); PG8_BAR; PG8_MMA(0, 0, At, B0); PG8_MMA(0, 1, At, B1); PG8_BAR; PG8_SCHED;
;             PG8_LDA(At, 0, 1); PG8_STAGE(PG8_SB(0, 0), b2, voffB); PG8_STAGE(PG8_SB(0, 1), b2 + hstep, voffB); PG8_STAGE(PG8_SA(0, 0), a2, voffA);
.LBB0_134:
	s_add_u32 s26, s24, 0xfffc0080
	s_addc_u32 s27, s25, -1
	s_add_i32 s51, 0, 0x10000
	s_cmp_eq_u32 s50, 12
	s_cselect_b32 s29, s17, s27
	s_cselect_b32 s28, s23, s26
	v_add_u32_e32 v0, s51, v183
	s_cselect_b32 s27, s15, s49
	s_cselect_b32 s26, s33, s48
	s_add_i32 s54, 0, 0x14000
	ds_read_b128 v[142:145], v0
	ds_read_b128 v[146:149], v0 offset:1024
	ds_read_b128 v[150:153], v0 offset:2048
	ds_read_b128 v[154:157], v0 offset:3072
	v_add_u32_e32 v0, s54, v183
	ds_read_b128 v[158:161], v0
	ds_read_b128 v[162:165], v0 offset:1024
	ds_read_b128 v[166:169], v0 offset:2048
	ds_read_b128 v[170:173], v0 offset:3072
	v_lshl_add_u64 v[208:209], s[24:25], 0, v[138:139]
	s_add_i32 m0, s39, 0xc000
	ds_read_b128 v[174:177], v186
	ds_read_b128 v[178:181], v186 offset:1024
	ds_read_b128 v[188:191], v186 offset:2048
	ds_read_b128 v[192:195], v186 offset:3072
	ds_read_b128 v[196:199], v186 offset:4096
	ds_read_b128 v[200:203], v186 offset:5120
	ds_read_b128 v[204:207], v186 offset:6144
	ds_read_b128 v[218:221], v186 offset:7168
	global_load_lds_dwordx4 v[208:209], off
	v_lshl_add_u64 v[208:209], s[24:25], 0, v[140:141]
	s_add_i32 m0, s39, 0xe000
	s_nop 0
	global_load_lds_dwordx4 v[208:209], off
	s_waitcnt vmcnt(8)
	s_waitcnt lgkmcnt(0)
	s_setprio 1
	s_barrier
	s_waitcnt lgkmcnt(0)
	v_mfma_f32_16x16x32_bf16 v[126:129], v[142:145], v[174:177], v[126:129]
	v_mfma_f32_16x16x32_bf16 v[122:125], v[150:153], v[174:177], v[122:125]
	v_mfma_f32_16x16x32_bf16 v[110:113], v[142:145], v[188:191], v[110:113]
	v_mfma_f32_16x16x32_bf16 v[106:109], v[150:153], v[188:191], v[106:109]
	v_mfma_f32_16x16x32_bf16 v[94:97], v[142:145], v[196:199], v[94:97]
	v_mfma_f32_16x16x32_bf16 v[90:93], v[150:153], v[196:199], v[90:93]
	v_mfma_f32_16x16x32_bf16 v[78:81], v[142:145], v[204:207], v[78:81]
	v_mfma_f32_16x16x32_bf16 v[74:77], v[150:153], v[204:207], v[74:77]
	v_mfma_f32_16x16x32_bf16 v[126:129], v[146:149], v[178:181], v[126:129]
	v_mfma_f32_16x16x32_bf16 v[122:125], v[154:157], v[178:181], v[122:125]
	v_mfma_f32_16x16x32_bf16 v[110:113], v[146:149], v[192:195], v[110:113]
	v_mfma_f32_16x16x32_bf16 v[106:109], v[154:157], v[192:195], v[106:109]
	v_mfma_f32_16x16x32_bf16 v[94:97], v[146:149], v[200:203], v[94:97]
	v_mfma_f32_16x16x32_bf16 v[90:93], v[154:157], v[200:203], v[90:93]
	v_mfma_f32_16x16x32_bf16 v[78:81], v[146:149], v[218:221], v[78:81]
	v_mfma_f32_16x16x32_bf16 v[74:77], v[154:157], v[218:221], v[74:77]
	v_mfma_f32_16x16x32_bf16 v[118:121], v[158:161], v[174:177], v[118:121]
	v_mfma_f32_16x16x32_bf16 v[114:117], v[166:169], v[174:177], v[114:117]
	v_mfma_f32_16x16x32_bf16 v[102:105], v[158:161], v[188:191], v[102:105]
	v_mfma_f32_16x16x32_bf16 v[98:101], v[166:169], v[188:191], v[98:101]
	v_mfma_f32_16x16x32_bf16 v[86:89], v[158:161], v[196:199], v[86:89]
	v_mfma_f32_16x16x32_bf16 v[82:85], v[166:169], v[196:199], v[82:85]
	v_mfma_f32_16x16x32_bf16 v[70:73], v[158:161], v[204:207], v[70:73]
	v_mfma_f32_16x16x32_bf16 v[66:69], v[166:169], v[204:207], v[66:69]
	v_mfma_f32_16x16x32_bf16 v[118:121], v[162:165], v[178:181], v[118:121]
	v_mfma_f32_16x16x32_bf16 v[114:117], v[170:173], v[178:181], v[114:117]
	v_mfma_f32_16x16x32_bf16 v[102:105], v[162:165], v[192:195], v[102:105]
	v_mfma_f32_16x16x32_bf16 v[98:101], v[170:173], v[192:195], v[98:101]
	v_mfma_f32_16x16x32_bf16 v[86:89], v[162:165], v[200:203], v[86:89]
	v_mfma_f32_16x16x32_bf16 v[82:85], v[170:173], v[200:203], v[82:85]
	v_mfma_f32_16x16x32_bf16 v[70:73], v[162:165], v[218:221], v[70:73]
	v_mfma_f32_16x16x32_bf16 v[66:69], v[170:173], v[218:221], v[66:69]
	s_barrier
	s_setprio 0
	s_add_i32 s51, s51, s35
	v_lshl_add_u64 v[208:209], s[26:27], 0, v[134:135]
	s_mov_b32 m0, s51
	ds_read_b128 v[174:177], v186 offset:16384
	ds_read_b128 v[178:181], v186 offset:17408
	ds_read_b128 v[188:191], v186 offset:18432
	ds_read_b128 v[192:195], v186 offset:19456
	ds_read_b128 v[196:199], v186 offset:20480
	ds_read_b128 v[200:203], v186 offset:21504
	ds_read_b128 v[204:207], v186 offset:22528
	ds_read_b128 v[218:221], v186 offset:23552
	global_load_lds_dwordx4 v[208:209], off
	s_add_i32 m0, s51, 0x2000
	s_add_u32 s52, s26, 0x40000
	v_lshl_add_u64 v[210:211], s[26:27], 0, v[130:131]
	s_addc_u32 s53, s27, 0
	s_add_i32 s51, s54, s35
	global_load_lds_dwordx4 v[210:211], off
	v_lshl_add_u64 v[212:213], s[52:53], 0, v[134:135]
	s_mov_b32 m0, s51
	v_lshl_add_u64 v[214:215], s[28:29], 0, v[132:133]
	global_load_lds_dwordx4 v[212:213], off
	v_lshl_add_u64 v[212:213], s[52:53], 0, v[130:131]
	s_add_i32 m0, s51, 0x2000
	s_nop 0
	global_load_lds_dwordx4 v[212:213], off
	v_lshl_add_u64 v[212:213], s[28:29], 0, v[136:137]
	s_mov_b32 m0, s39
	s_nop 0
	global_load_lds_dwordx4 v[212:213], off
	s_mov_b32 m0, s40
	s_nop 0
	global_load_lds_dwordx4 v[214:215], off
	s_waitcnt vmcnt(8)
	s_waitcnt lgkmcnt(0)
	s_setprio 1
	s_barrier
; #define PG8_STAGE(bufoff, gbase, voff) do { _Pragma("unroll") for (int _i = 0; _i < 2; ++_i) \
;         __builtin_amdgcn_global_load_lds((const unsigned*)((const char*)(gbase) + (voff)[_i]), (PG8_LAS unsigned*)(lds + (bufoff) + ldsw + _i * 8192), 16, 0, 0); } while (0)
; #define PG8_LDA(dst, b, h) do { _Pragma("unroll") for (int m = 0; m < 4; ++m) _Pragma("unroll") for (int k = 0; k < 2; ++k) dst[m][k] = *(const PG8_LAS bf16x8*)(lds + PG8_SA(b, h) + aoff + m * 2048 + k * 1024); } while (0)
; #define PG8_LDB(dst, b, h) do { _Pragma("unroll") for (int n = 0; n < 2; ++n) _Pragma("unroll") for (int k = 0; k < 2; ++k) dst[n][k] = *(const PG8_LAS bf16x8*)(lds + PG8_SB(b, h) + boff + n * 2048 + k * 1024); } while (0)
; #define PG8_MMA(ai, bj, At, Bt) do { __builtin_amdgcn_s_setprio(1); _Pragma("unroll") for (int m = 0; m < 4; ++m) _Pragma("unroll") for (int n = 0; n < 2; ++n) _Pragma("unroll") for (int k = 0; k < 2; ++k) \
;         acc[ai][bj][m][n] = __builtin_amdgcn_mfma_f32_16x16x32_bf16(Bt[n][k], At[m][k], acc[ai][bj][m][n], 0, 0, 0); __builtin_amdgcn_s_setprio(0); } while (0)
; #define PG8_WAIT_V(n) asm volatile("s_waitcnt vmcnt(" #n ")" ::: "memory")
; #define PG8_WAIT_L(n) asm volatile("s_waitcnt lgkmcnt(" #n ")" ::: "memory")
; #define PG8_BAR __builtin_amdgcn_s_barrier()
; #define PG8_SCHED __builtin_amdgcn_sched_barrier(0)
; template <class Epi, class Sched, bool ALIGN_EPI = false, bool SP2 = false>
; __device__ __forceinline__ void gemm_phase(PG8_LAS unsigned char* lds, const Gemm g, const Sched& S, const Epi& E, const int wv) {
;     ...
;             PG8_WAIT_V(8); PG8_WAIT_L(0); PG8_BAR; PG8_MMA(1, 0, At, B0); PG8_MMA(1, 1, At, B1); PG8_BAR; PG8_SCHED;
;             PG8_LDB(B0, 1, 0); PG8_LDB(B1, 1, 1); PG8_SCHED; PG8_LDA(At, 1, 0); PG8_STAGE(PG8_SA(0, 1), a2 + hstep, voffA);
;             PG8_WAIT_V(8); PG8_WAIT_L(0); PG8_BAR; PG8_MMA(0, 0, At, B0); PG8_MMA(0, 1, At, B1); PG8_BAR; PG8_SCHED;
	s_waitcnt lgkmcnt(0)
	v_mfma_f32_16x16x32_bf16 v[62:65], v[142:145], v[174:177], v[62:65]
	v_mfma_f32_16x16x32_bf16 v[58:61], v[150:153], v[174:177], v[58:61]
	v_mfma_f32_16x16x32_bf16 v[46:49], v[142:145], v[188:191], v[46:49]
	v_mfma_f32_16x16x32_bf16 v[42:45], v[150:153], v[188:191], v[42:45]
	v_mfma_f32_16x16x32_bf16 v[30:33], v[142:145], v[196:199], v[30:33]
	v_mfma_f32_16x16x32_bf16 v[26:29], v[150:153], v[196:199], v[26:29]
	v_mfma_f32_16x16x32_bf16 v[14:17], v[142:145], v[204:207], v[14:17]
	v_mfma_f32_16x16x32_bf16 v[10:13], v[150:153], v[204:207], v[10:13]
	v_mfma_f32_16x16x32_bf16 v[62:65], v[146:149], v[178:181], v[62:65]
	v_mfma_f32_16x16x32_bf16 v[58:61], v[154:157], v[178:181], v[58:61]
	v_mfma_f32_16x16x32_bf16 v[46:49], v[146:149], v[192:195], v[46:49]
	v_mfma_f32_16x16x32_bf16 v[42:45], v[154:157], v[192:195], v[42:45]
	v_mfma_f32_16x16x32_bf16 v[30:33], v[146:149], v[200:203], v[30:33]
	v_mfma_f32_16x16x32_bf16 v[26:29], v[154:157], v[200:203], v[26:29]
	v_mfma_f32_16x16x32_bf16 v[14:17], v[146:149], v[218:221], v[14:17]
	v_mfma_f32_16x16x32_bf16 v[10:13], v[154:157], v[218:221], v[10:13]
	v_mfma_f32_16x16x32_bf16 v[54:57], v[158:161], v[174:177], v[54:57]
	v_mfma_f32_16x16x32_bf16 v[50:53], v[166:169], v[174:177], v[50:53]
	v_mfma_f32_16x16x32_bf16 v[38:41], v[158:161], v[188:191], v[38:41]
	v_mfma_f32_16x16x32_bf16 v[34:37], v[166:169], v[188:191], v[34:37]
	v_mfma_f32_16x16x32_bf16 v[22:25], v[158:161], v[196:199], v[22:25]
	v_mfma_f32_16x16x32_bf16 v[18:21], v[166:169], v[196:199], v[18:21]
	v_mfma_f32_16x16x32_bf16 v[6:9], v[158:161], v[204:207], v[6:9]
	v_mfma_f32_16x16x32_bf16 v[2:5], v[166:169], v[204:207], v[2:5]
	v_mfma_f32_16x16x32_bf16 v[54:57], v[162:165], v[178:181], v[54:57]
	v_mfma_f32_16x16x32_bf16 v[50:53], v[170:173], v[178:181], v[50:53]
	v_mfma_f32_16x16x32_bf16 v[38:41], v[162:165], v[192:195], v[38:41]
	v_mfma_f32_16x16x32_bf16 v[34:37], v[170:173], v[192:195], v[34:37]
	v_mfma_f32_16x16x32_bf16 v[22:25], v[162:165], v[200:203], v[22:25]
	v_mfma_f32_16x16x32_bf16 v[18:21], v[170:173], v[200:203], v[18:21]
	v_mfma_f32_16x16x32_bf16 v[6:9], v[162:165], v[218:221], v[6:9]
	v_mfma_f32_16x16x32_bf16 v[2:5], v[170:173], v[218:221], v[2:5]
	s_barrier
	s_setprio 0
	s_add_i32 s51, 0, 0x18000
	v_add_u32_e32 v0, s51, v183
	s_add_i32 s52, 0, 0x1c000
	ds_read_b128 v[142:145], v0
	ds_read_b128 v[146:149], v0 offset:1024
	ds_read_b128 v[150:153], v0 offset:2048
	ds_read_b128 v[154:157], v0 offset:3072
	v_add_u32_e32 v0, s52, v183
	ds_read_b128 v[158:161], v0
	ds_read_b128 v[162:165], v0 offset:1024
	ds_read_b128 v[166:169], v0 offset:2048
	ds_read_b128 v[170:173], v0 offset:3072
	s_add_u32 s28, s28, 0x40000
	s_addc_u32 s29, s29, 0
	s_mov_b32 m0, s41
	v_lshl_add_u64 v[216:217], s[28:29], 0, v[136:137]
	ds_read_b128 v[174:177], v186 offset:32768
	ds_read_b128 v[178:181], v186 offset:33792
	ds_read_b128 v[188:191], v186 offset:34816
	ds_read_b128 v[192:195], v186 offset:35840
	ds_read_b128 v[196:199], v186 offset:36864
	ds_read_b128 v[200:203], v186 offset:37888
	ds_read_b128 v[204:207], v186 offset:38912
	ds_read_b128 v[218:221], v186 offset:39936
	global_load_lds_dwordx4 v[216:217], off
	v_lshl_add_u64 v[216:217], s[28:29], 0, v[132:133]
	s_mov_b32 m0, s42
	s_nop 0
	global_load_lds_dwordx4 v[216:217], off
	s_waitcnt vmcnt(8)
	s_waitcnt lgkmcnt(0)
	s_setprio 1
	s_barrier
	s_waitcnt lgkmcnt(0)
	v_mfma_f32_16x16x32_bf16 v[126:129], v[142:145], v[174:177], v[126:129]
	v_mfma_f32_16x16x32_bf16 v[122:125], v[150:153], v[174:177], v[122:125]
	v_mfma_f32_16x16x32_bf16 v[110:113], v[142:145], v[188:191], v[110:113]
	v_mfma_f32_16x16x32_bf16 v[106:109], v[150:153], v[188:191], v[106:109]
	v_mfma_f32_16x16x32_bf16 v[94:97], v[142:145], v[196:199], v[94:97]
	v_mfma_f32_16x16x32_bf16 v[90:93], v[150:153], v[196:199], v[90:93]
	v_mfma_f32_16x16x32_bf16 v[78:81], v[142:145], v[204:207], v[78:81]
	v_mfma_f32_16x16x32_bf16 v[74:77], v[150:153], v[204:207], v[74:77]
	v_mfma_f32_16x16x32_bf16 v[126:129], v[146:149], v[178:181], v[126:129]
	v_mfma_f32_16x16x32_bf16 v[122:125], v[154:157], v[178:181], v[122:125]
	v_mfma_f32_16x16x32_bf16 v[110:113], v[146:149], v[192:195], v[110:113]
	v_mfma_f32_16x16x32_bf16 v[106:109], v[154:157], v[192:195], v[106:109]
	v_mfma_f32_16x16x32_bf16 v[94:97], v[146:149], v[200:203], v[94:97]
	v_mfma_f32_16x16x32_bf16 v[90:93], v[154:157], v[200:203], v[90:93]
	v_mfma_f32_16x16x32_bf16 v[78:81], v[146:149], v[218:221], v[78:81]
	v_mfma_f32_16x16x32_bf16 v[74:77], v[154:157], v[218:221], v[74:77]
	v_mfma_f32_16x16x32_bf16 v[118:121], v[158:161], v[174:177], v[118:121]
	v_mfma_f32_16x16x32_bf16 v[114:117], v[166:169], v[174:177], v[114:117]
	v_mfma_f32_16x16x32_bf16 v[102:105], v[158:161], v[188:191], v[102:105]
	v_mfma_f32_16x16x32_bf16 v[98:101], v[166:169], v[188:191], v[98:101]
	v_mfma_f32_16x16x32_bf16 v[86:89], v[158:161], v[196:199], v[86:89]
	v_mfma_f32_16x16x32_bf16 v[82:85], v[166:169], v[196:199], v[82:85]
	v_mfma_f32_16x16x32_bf16 v[70:73], v[158:161], v[204:207], v[70:73]
	v_mfma_f32_16x16x32_bf16 v[66:69], v[166:169], v[204:207], v[66:69]
	v_mfma_f32_16x16x32_bf16 v[118:121], v[162:165], v[178:181], v[118:121]
	v_mfma_f32_16x16x32_bf16 v[114:117], v[170:173], v[178:181], v[114:117]
	v_mfma_f32_16x16x32_bf16 v[102:105], v[162:165], v[192:195], v[102:105]
	v_mfma_f32_16x16x32_bf16 v[98:101], v[170:173], v[192:195], v[98:101]
	v_mfma_f32_16x16x32_bf16 v[86:89], v[162:165], v[200:203], v[86:89]
	v_mfma_f32_16x16x32_bf16 v[82:85], v[170:173], v[200:203], v[82:85]
	v_mfma_f32_16x16x32_bf16 v[70:73], v[162:165], v[218:221], v[70:73]
	v_mfma_f32_16x16x32_bf16 v[66:69], v[170:173], v[218:221], v[66:69]
	s_barrier
; #define PG8_STAGE(bufoff, gbase, voff) do { _Pragma("unroll") for (int _i = 0; _i < 2; ++_i) \
;         __builtin_amdgcn_global_load_lds((const unsigned*)((const char*)(gbase) + (voff)[_i]), (PG8_LAS unsigned*)(lds + (bufoff) + ldsw + _i * 8192), 16, 0, 0); } while (0)
; #define PG8_LDA(dst, b, h) do { _Pragma("unroll") for (int m = 0; m < 4; ++m) _Pragma("unroll") for (int k = 0; k < 2; ++k) dst[m][k] = *(const PG8_LAS bf16x8*)(lds + PG8_SA(b, h) + aoff + m * 2048 + k * 1024); } while (0)
; #define PG8_MMA(ai, bj, At, Bt) do { __builtin_amdgcn_s_setprio(1); _Pragma("unroll") for (int m = 0; m < 4; ++m) _Pragma("unroll") for (int n = 0; n < 2; ++n) _Pragma("unroll") for (int k = 0; k < 2; ++k) \
;         acc[ai][bj][m][n] = __builtin_amdgcn_mfma_f32_16x16x32_bf16(Bt[n][k], At[m][k], acc[ai][bj][m][n], 0, 0, 0); __builtin_amdgcn_s_setprio(0); } while (0)
; #define PG8_WAIT_V(n) asm volatile("s_waitcnt vmcnt(" #n ")" ::: "memory")
; #define PG8_WAIT_L(n) asm volatile("s_waitcnt lgkmcnt(" #n ")" ::: "memory")
; #define PG8_BAR __builtin_amdgcn_s_barrier()
; #define PG8_SCHED __builtin_amdgcn_sched_barrier(0)
; template <class Epi, class Sched, bool ALIGN_EPI = false, bool SP2 = false>
; __device__ __forceinline__ void gemm_phase(PG8_LAS unsigned char* lds, const Gemm g, const Sched& S, const Epi& E, const int wv) {
;     ...
;             PG8_LDA(At, 1, 1); PG8_STAGE(PG8_SB(1, 0), b3, voffB); PG8_STAGE(PG8_SB(1, 1), b3 + hstep, voffB); PG8_STAGE(PG8_SA(1, 0), a3, voffA);
;             PG8_WAIT_V(8); PG8_WAIT_L(0); PG8_BAR; PG8_MMA(1, 0, At, B0); PG8_MMA(1, 1, At, B1); PG8_BAR; PG8_SCHED;
	s_setprio 0
	s_add_i32 s28, s51, s35
	v_lshl_add_u64 v[208:209], v[208:209], 0, s[2:3]
	s_mov_b32 m0, s28
	ds_read_b128 v[174:177], v186 offset:49152
	ds_read_b128 v[178:181], v186 offset:50176
	ds_read_b128 v[188:191], v186 offset:51200
	ds_read_b128 v[192:195], v186 offset:52224
	ds_read_b128 v[196:199], v186 offset:53248
	ds_read_b128 v[200:203], v186 offset:54272
	ds_read_b128 v[204:207], v186 offset:55296
	ds_read_b128 v[218:221], v186 offset:56320
	global_load_lds_dwordx4 v[208:209], off
	s_add_i32 m0, s28, 0x2000
	s_add_u32 s26, s26, 0x40080
	v_lshl_add_u64 v[208:209], v[210:211], 0, s[2:3]
	s_addc_u32 s27, s27, 0
	s_add_i32 s28, s52, s35
	global_load_lds_dwordx4 v[208:209], off
	v_lshl_add_u64 v[208:209], s[26:27], 0, v[134:135]
	s_mov_b32 m0, s28
	s_nop 0
	global_load_lds_dwordx4 v[208:209], off
	v_lshl_add_u64 v[208:209], s[26:27], 0, v[130:131]
	s_add_i32 m0, s28, 0x2000
	s_nop 0
	global_load_lds_dwordx4 v[208:209], off
	v_lshl_add_u64 v[208:209], v[212:213], 0, s[2:3]
	s_mov_b32 m0, s44
	s_nop 0
	global_load_lds_dwordx4 v[208:209], off
	v_lshl_add_u64 v[208:209], v[214:215], 0, s[2:3]
	s_mov_b32 m0, s45
	s_nop 0
	global_load_lds_dwordx4 v[208:209], off
	s_waitcnt vmcnt(8)
	s_waitcnt lgkmcnt(0)
	s_setprio 1
	s_barrier
	s_waitcnt lgkmcnt(0)
	v_mfma_f32_16x16x32_bf16 v[62:65], v[142:145], v[174:177], v[62:65]
	v_mfma_f32_16x16x32_bf16 v[58:61], v[150:153], v[174:177], v[58:61]
	v_mfma_f32_16x16x32_bf16 v[46:49], v[142:145], v[188:191], v[46:49]
	v_mfma_f32_16x16x32_bf16 v[42:45], v[150:153], v[188:191], v[42:45]
	v_mfma_f32_16x16x32_bf16 v[30:33], v[142:145], v[196:199], v[30:33]
	v_mfma_f32_16x16x32_bf16 v[26:29], v[150:153], v[196:199], v[26:29]
	v_mfma_f32_16x16x32_bf16 v[14:17], v[142:145], v[204:207], v[14:17]
	v_mfma_f32_16x16x32_bf16 v[10:13], v[150:153], v[204:207], v[10:13]
	v_mfma_f32_16x16x32_bf16 v[62:65], v[146:149], v[178:181], v[62:65]
	v_mfma_f32_16x16x32_bf16 v[58:61], v[154:157], v[178:181], v[58:61]
	v_mfma_f32_16x16x32_bf16 v[46:49], v[146:149], v[192:195], v[46:49]
	v_mfma_f32_16x16x32_bf16 v[42:45], v[154:157], v[192:195], v[42:45]
	v_mfma_f32_16x16x32_bf16 v[30:33], v[146:149], v[200:203], v[30:33]
	v_mfma_f32_16x16x32_bf16 v[26:29], v[154:157], v[200:203], v[26:29]
	v_mfma_f32_16x16x32_bf16 v[14:17], v[146:149], v[218:221], v[14:17]
	v_mfma_f32_16x16x32_bf16 v[10:13], v[154:157], v[218:221], v[10:13]
	v_mfma_f32_16x16x32_bf16 v[54:57], v[158:161], v[174:177], v[54:57]
	v_mfma_f32_16x16x32_bf16 v[50:53], v[166:169], v[174:177], v[50:53]
	v_mfma_f32_16x16x32_bf16 v[38:41], v[158:161], v[188:191], v[38:41]
	v_mfma_f32_16x16x32_bf16 v[34:37], v[166:169], v[188:191], v[34:37]
	v_mfma_f32_16x16x32_bf16 v[22:25], v[158:161], v[196:199], v[22:25]
	v_mfma_f32_16x16x32_bf16 v[18:21], v[166:169], v[196:199], v[18:21]
	v_mfma_f32_16x16x32_bf16 v[6:9], v[158:161], v[204:207], v[6:9]
	v_mfma_f32_16x16x32_bf16 v[2:5], v[166:169], v[204:207], v[2:5]
	v_mfma_f32_16x16x32_bf16 v[54:57], v[162:165], v[178:181], v[54:57]
	v_mfma_f32_16x16x32_bf16 v[50:53], v[170:173], v[178:181], v[50:53]
	v_mfma_f32_16x16x32_bf16 v[38:41], v[162:165], v[192:195], v[38:41]
	v_mfma_f32_16x16x32_bf16 v[34:37], v[170:173], v[192:195], v[34:37]
	v_mfma_f32_16x16x32_bf16 v[22:25], v[162:165], v[200:203], v[22:25]
	v_mfma_f32_16x16x32_bf16 v[18:21], v[170:173], v[200:203], v[18:21]
	v_mfma_f32_16x16x32_bf16 v[6:9], v[162:165], v[218:221], v[6:9]
	v_mfma_f32_16x16x32_bf16 v[2:5], v[170:173], v[218:221], v[2:5]
	s_barrier
	s_setprio 0
	s_add_i32 s50, s50, 2
	s_add_u32 s24, s24, 0x100
	s_addc_u32 s25, s25, 0
	s_add_u32 s48, s48, 0x100
	s_addc_u32 s49, s49, 0
	s_cmp_gt_u32 s50, 13
	s_cbranch_scc0 .LBB0_134
	s_and_b64 vcc, exec, s[10:11]
	s_cbranch_vccz .LBB0_137
	s_barrier

; #define PG8_STAGE(bufoff, gbase, voff) do { _Pragma("unroll") for (int _i = 0; _i < 2; ++_i) \
;         __builtin_amdgcn_global_load_lds((const unsigned*)((const char*)(gbase) + (voff)[_i]), (PG8_LAS unsigned*)(lds + (bufoff) + ldsw + _i * 8192), 16, 0, 0); } while (0)
; #define PG8_LDA(dst, b, h) do { _Pragma("unroll") for (int m = 0; m < 4; ++m) _Pragma("unroll") for (int k = 0; k < 2; ++k) dst[m][k] = *(const PG8_LAS bf16x8*)(lds + PG8_SA(b, h) + aoff + m * 2048 + k * 1024); } while (0)
; #define PG8_LDB(dst, b, h) do { _Pragma("unroll") for (int n = 0; n < 2; ++n) _Pragma("unroll") for (int k = 0; k < 2; ++k) dst[n][k] = *(const PG8_LAS bf16x8*)(lds + PG8_SB(b, h) + boff + n * 2048 + k * 1024); } while (0)
; #define PG8_MMA(ai, bj, At, Bt) do { __builtin_amdgcn_s_setprio(1); _Pragma("unroll") for (int m = 0; m < 4; ++m) _Pragma("unroll") for (int n = 0; n < 2; ++n) _Pragma("unroll") for (int k = 0; k < 2; ++k) \
;         acc[ai][bj][m][n] = __builtin_amdgcn_mfma_f32_16x16x32_bf16(Bt[n][k], At[m][k], acc[ai][bj][m][n], 0, 0, 0); __builtin_amdgcn_s_setprio(0); } while (0)
; #define PG8_WAIT_V(n) asm volatile("s_waitcnt vmcnt(" #n ")" ::: "memory")
; #define PG8_WAIT_L(n) asm volatile("s_waitcnt lgkmcnt(" #n ")" ::: "memory")
; #define PG8_BAR __builtin_amdgcn_s_barrier()
; #define PG8_SCHED __builtin_amdgcn_sched_barrier(0)
; template <class Epi, class Sched, bool ALIGN_EPI = false, bool SP2 = false>
; __device__ __forceinline__ void gemm_phase(PG8_LAS unsigned char* lds, const Gemm g, const Sched& S, const Epi& E, const int wv) {
;     ...
;             const bool last = (t == nt - 2);
;             const char* a1 = cA + (size_t)(t + 1) * kstep;
;             const char* a2 = last ? nA : cA + (size_t)(t + 2) * kstep; const char* b2 = last ? nB : cB + (size_t)(t + 2) * kstep;
;             const char* a3 = a2 + kstep; const char* b3 = b2 + kstep;
;             if (last && has_next) S.a_ready(nxt);
;             if constexpr (SP2) {
;             PG8_LDB(B0, 0, 0); PG8_LDB(B1, 0, 1); PG8_SCHED; PG8_LDA(At, 0, 0); PG8_STAGE(PG8_SA(1, 1), a1 + hstep, voffA);
;             PG8_WAIT_V(8); PG8_WAIT_L(0); PG8_BAR; PG8_MMA(0, 0, At, B0); PG8_MMA(0, 1, At, B1); PG8_BAR; PG8_SCHED;
;             PG8_LDA(At, 0, 1); PG8_STAGE(PG8_SB(0, 0), b2, voffB); PG8_STAGE(PG8_SB(0, 1), b2 + hstep, voffB); PG8_STAGE(PG8_SA(0, 0), a2, voffA);
.LBB0_156:
	s_add_u32 s20, s18, 0xfffc0080
	s_addc_u32 s21, s19, -1
	s_add_i32 s45, 0, 0x10000
	s_cmp_eq_u32 s44, 12
	s_cselect_b32 s23, s11, s21
	s_cselect_b32 s22, s40, s20
	v_add_u32_e32 v152, s45, v155
	s_cselect_b32 s21, s9, s43
	s_cselect_b32 s20, s41, s42
	s_add_i32 s48, 0, 0x14000
	ds_read_b128 v[140:143], v152
	ds_read_b128 v[144:147], v152 offset:1024
	ds_read_b128 v[148:151], v152 offset:2048
	ds_read_b128 v[158:161], v152 offset:3072
	v_add_u32_e32 v152, s48, v155
	ds_read_b128 v[162:165], v152
	ds_read_b128 v[166:169], v152 offset:1024
	ds_read_b128 v[170:173], v152 offset:2048
	ds_read_b128 v[174:177], v152 offset:3072
	v_lshl_add_u64 v[152:153], s[18:19], 0, v[136:137]
	s_add_i32 m0, s17, 0xc000
	ds_read_b128 v[178:181], v157
	ds_read_b128 v[182:185], v157 offset:1024
	ds_read_b128 v[186:189], v157 offset:2048
	ds_read_b128 v[190:193], v157 offset:3072
	ds_read_b128 v[194:197], v157 offset:4096
	ds_read_b128 v[198:201], v157 offset:5120
	ds_read_b128 v[202:205], v157 offset:6144
	ds_read_b128 v[206:209], v157 offset:7168
	global_load_lds_dwordx4 v[152:153], off
	v_lshl_add_u64 v[152:153], s[18:19], 0, v[138:139]
	s_add_i32 m0, s17, 0xe000
	s_nop 0
	global_load_lds_dwordx4 v[152:153], off
	s_waitcnt vmcnt(8)
	s_waitcnt lgkmcnt(0)
	s_setprio 1
	s_barrier
	s_waitcnt lgkmcnt(0)
	v_mfma_f32_16x16x32_bf16 v[126:129], v[140:143], v[178:181], v[126:129]
	v_mfma_f32_16x16x32_bf16 v[122:125], v[148:151], v[178:181], v[122:125]
	v_mfma_f32_16x16x32_bf16 v[118:121], v[140:143], v[186:189], v[118:121]
	v_mfma_f32_16x16x32_bf16 v[114:117], v[148:151], v[186:189], v[114:117]
	v_mfma_f32_16x16x32_bf16 v[98:101], v[140:143], v[194:197], v[98:101]
	v_mfma_f32_16x16x32_bf16 v[90:93], v[148:151], v[194:197], v[90:93]
	v_mfma_f32_16x16x32_bf16 v[78:81], v[140:143], v[202:205], v[78:81]
	v_mfma_f32_16x16x32_bf16 v[74:77], v[148:151], v[202:205], v[74:77]
	v_mfma_f32_16x16x32_bf16 v[126:129], v[144:147], v[182:185], v[126:129]
	v_mfma_f32_16x16x32_bf16 v[122:125], v[158:161], v[182:185], v[122:125]
	v_mfma_f32_16x16x32_bf16 v[118:121], v[144:147], v[190:193], v[118:121]
	v_mfma_f32_16x16x32_bf16 v[114:117], v[158:161], v[190:193], v[114:117]
	v_mfma_f32_16x16x32_bf16 v[98:101], v[144:147], v[198:201], v[98:101]
	v_mfma_f32_16x16x32_bf16 v[90:93], v[158:161], v[198:201], v[90:93]
	v_mfma_f32_16x16x32_bf16 v[78:81], v[144:147], v[206:209], v[78:81]
	v_mfma_f32_16x16x32_bf16 v[74:77], v[158:161], v[206:209], v[74:77]
	v_mfma_f32_16x16x32_bf16 v[110:113], v[162:165], v[178:181], v[110:113]
	v_mfma_f32_16x16x32_bf16 v[106:109], v[170:173], v[178:181], v[106:109]
	v_mfma_f32_16x16x32_bf16 v[102:105], v[162:165], v[186:189], v[102:105]
	v_mfma_f32_16x16x32_bf16 v[94:97], v[170:173], v[186:189], v[94:97]
	v_mfma_f32_16x16x32_bf16 v[86:89], v[162:165], v[194:197], v[86:89]
	v_mfma_f32_16x16x32_bf16 v[82:85], v[170:173], v[194:197], v[82:85]
	v_mfma_f32_16x16x32_bf16 v[70:73], v[162:165], v[202:205], v[70:73]
	v_mfma_f32_16x16x32_bf16 v[66:69], v[170:173], v[202:205], v[66:69]
	v_mfma_f32_16x16x32_bf16 v[110:113], v[166:169], v[182:185], v[110:113]
	v_mfma_f32_16x16x32_bf16 v[106:109], v[174:177], v[182:185], v[106:109]
	v_mfma_f32_16x16x32_bf16 v[102:105], v[166:169], v[190:193], v[102:105]
	v_mfma_f32_16x16x32_bf16 v[94:97], v[174:177], v[190:193], v[94:97]
	v_mfma_f32_16x16x32_bf16 v[86:89], v[166:169], v[198:201], v[86:89]
	v_mfma_f32_16x16x32_bf16 v[82:85], v[174:177], v[198:201], v[82:85]
	v_mfma_f32_16x16x32_bf16 v[70:73], v[166:169], v[206:209], v[70:73]
	v_mfma_f32_16x16x32_bf16 v[66:69], v[174:177], v[206:209], v[66:69]
	s_barrier
	s_setprio 0
	s_add_i32 s45, s45, s24
	v_lshl_add_u64 v[152:153], s[20:21], 0, v[0:1]
	s_mov_b32 m0, s45
	ds_read_b128 v[178:181], v157 offset:16384
	ds_read_b128 v[182:185], v157 offset:17408
	ds_read_b128 v[186:189], v157 offset:18432
	ds_read_b128 v[190:193], v157 offset:19456
	ds_read_b128 v[194:197], v157 offset:20480
	ds_read_b128 v[198:201], v157 offset:21504
	ds_read_b128 v[202:205], v157 offset:22528
	ds_read_b128 v[206:209], v157 offset:23552
	global_load_lds_dwordx4 v[152:153], off
	s_add_i32 m0, s45, 0x2000
	s_add_u32 s46, s20, 0x40000
	v_lshl_add_u64 v[210:211], s[20:21], 0, v[130:131]
	s_addc_u32 s47, s21, 0
	s_add_i32 s45, s48, s24
	global_load_lds_dwordx4 v[210:211], off
	v_lshl_add_u64 v[212:213], s[46:47], 0, v[0:1]
	s_mov_b32 m0, s45
	v_lshl_add_u64 v[214:215], s[22:23], 0, v[132:133]
	global_load_lds_dwordx4 v[212:213], off
	v_lshl_add_u64 v[212:213], s[46:47], 0, v[130:131]
	s_add_i32 m0, s45, 0x2000
	s_nop 0
	global_load_lds_dwordx4 v[212:213], off
	v_lshl_add_u64 v[212:213], s[22:23], 0, v[134:135]
	s_mov_b32 m0, s17
	s_nop 0
	global_load_lds_dwordx4 v[212:213], off
	s_mov_b32 m0, s26
	s_nop 0
	global_load_lds_dwordx4 v[214:215], off
	s_waitcnt vmcnt(8)
	s_waitcnt lgkmcnt(0)
	s_setprio 1
	s_barrier
; #define PG8_STAGE(bufoff, gbase, voff) do { _Pragma("unroll") for (int _i = 0; _i < 2; ++_i) \
;         __builtin_amdgcn_global_load_lds((const unsigned*)((const char*)(gbase) + (voff)[_i]), (PG8_LAS unsigned*)(lds + (bufoff) + ldsw + _i * 8192), 16, 0, 0); } while (0)
; #define PG8_LDA(dst, b, h) do { _Pragma("unroll") for (int m = 0; m < 4; ++m) _Pragma("unroll") for (int k = 0; k < 2; ++k) dst[m][k] = *(const PG8_LAS bf16x8*)(lds + PG8_SA(b, h) + aoff + m * 2048 + k * 1024); } while (0)
; #define PG8_LDB(dst, b, h) do { _Pragma("unroll") for (int n = 0; n < 2; ++n) _Pragma("unroll") for (int k = 0; k < 2; ++k) dst[n][k] = *(const PG8_LAS bf16x8*)(lds + PG8_SB(b, h) + boff + n * 2048 + k * 1024); } while (0)
; #define PG8_MMA(ai, bj, At, Bt) do { __builtin_amdgcn_s_setprio(1); _Pragma("unroll") for (int m = 0; m < 4; ++m) _Pragma("unroll") for (int n = 0; n < 2; ++n) _Pragma("unroll") for (int k = 0; k < 2; ++k) \
;         acc[ai][bj][m][n] = __builtin_amdgcn_mfma_f32_16x16x32_bf16(Bt[n][k], At[m][k], acc[ai][bj][m][n], 0, 0, 0); __builtin_amdgcn_s_setprio(0); } while (0)
; #define PG8_WAIT_V(n) asm volatile("s_waitcnt vmcnt(" #n ")" ::: "memory")
; #define PG8_WAIT_L(n) asm volatile("s_waitcnt lgkmcnt(" #n ")" ::: "memory")
; #define PG8_BAR __builtin_amdgcn_s_barrier()
; #define PG8_SCHED __builtin_amdgcn_sched_barrier(0)
; template <class Epi, class Sched, bool ALIGN_EPI = false, bool SP2 = false>
; __device__ __forceinline__ void gemm_phase(PG8_LAS unsigned char* lds, const Gemm g, const Sched& S, const Epi& E, const int wv) {
;     ...
;             PG8_WAIT_V(8); PG8_WAIT_L(0); PG8_BAR; PG8_MMA(1, 0, At, B0); PG8_MMA(1, 1, At, B1); PG8_BAR; PG8_SCHED;
;             PG8_LDB(B0, 1, 0); PG8_LDB(B1, 1, 1); PG8_SCHED; PG8_LDA(At, 1, 0); PG8_STAGE(PG8_SA(0, 1), a2 + hstep, voffA);
;             PG8_WAIT_V(8); PG8_WAIT_L(0); PG8_BAR; PG8_MMA(0, 0, At, B0); PG8_MMA(0, 1, At, B1); PG8_BAR; PG8_SCHED;
	s_waitcnt lgkmcnt(0)
	v_mfma_f32_16x16x32_bf16 v[62:65], v[140:143], v[178:181], v[62:65]
	v_mfma_f32_16x16x32_bf16 v[58:61], v[148:151], v[178:181], v[58:61]
	v_mfma_f32_16x16x32_bf16 v[46:49], v[140:143], v[186:189], v[46:49]
	v_mfma_f32_16x16x32_bf16 v[42:45], v[148:151], v[186:189], v[42:45]
	v_mfma_f32_16x16x32_bf16 v[30:33], v[140:143], v[194:197], v[30:33]
	v_mfma_f32_16x16x32_bf16 v[26:29], v[148:151], v[194:197], v[26:29]
	v_mfma_f32_16x16x32_bf16 v[14:17], v[140:143], v[202:205], v[14:17]
	v_mfma_f32_16x16x32_bf16 v[10:13], v[148:151], v[202:205], v[10:13]
	v_mfma_f32_16x16x32_bf16 v[62:65], v[144:147], v[182:185], v[62:65]
	v_mfma_f32_16x16x32_bf16 v[58:61], v[158:161], v[182:185], v[58:61]
	v_mfma_f32_16x16x32_bf16 v[46:49], v[144:147], v[190:193], v[46:49]
	v_mfma_f32_16x16x32_bf16 v[42:45], v[158:161], v[190:193], v[42:45]
	v_mfma_f32_16x16x32_bf16 v[30:33], v[144:147], v[198:201], v[30:33]
	v_mfma_f32_16x16x32_bf16 v[26:29], v[158:161], v[198:201], v[26:29]
	v_mfma_f32_16x16x32_bf16 v[14:17], v[144:147], v[206:209], v[14:17]
	v_mfma_f32_16x16x32_bf16 v[10:13], v[158:161], v[206:209], v[10:13]
	v_mfma_f32_16x16x32_bf16 v[54:57], v[162:165], v[178:181], v[54:57]
	v_mfma_f32_16x16x32_bf16 v[50:53], v[170:173], v[178:181], v[50:53]
	v_mfma_f32_16x16x32_bf16 v[38:41], v[162:165], v[186:189], v[38:41]
	v_mfma_f32_16x16x32_bf16 v[34:37], v[170:173], v[186:189], v[34:37]
	v_mfma_f32_16x16x32_bf16 v[22:25], v[162:165], v[194:197], v[22:25]
	v_mfma_f32_16x16x32_bf16 v[18:21], v[170:173], v[194:197], v[18:21]
	v_mfma_f32_16x16x32_bf16 v[6:9], v[162:165], v[202:205], v[6:9]
	v_mfma_f32_16x16x32_bf16 v[2:5], v[170:173], v[202:205], v[2:5]
	v_mfma_f32_16x16x32_bf16 v[54:57], v[166:169], v[182:185], v[54:57]
	v_mfma_f32_16x16x32_bf16 v[50:53], v[174:177], v[182:185], v[50:53]
	v_mfma_f32_16x16x32_bf16 v[38:41], v[166:169], v[190:193], v[38:41]
	v_mfma_f32_16x16x32_bf16 v[34:37], v[174:177], v[190:193], v[34:37]
	v_mfma_f32_16x16x32_bf16 v[22:25], v[166:169], v[198:201], v[22:25]
	v_mfma_f32_16x16x32_bf16 v[18:21], v[174:177], v[198:201], v[18:21]
	v_mfma_f32_16x16x32_bf16 v[6:9], v[166:169], v[206:209], v[6:9]
	v_mfma_f32_16x16x32_bf16 v[2:5], v[174:177], v[206:209], v[2:5]
	s_barrier
	s_setprio 0
	s_add_i32 s45, 0, 0x18000
	s_add_i32 s46, 0, 0x1c000
	v_add_u32_e32 v158, s45, v155
	v_add_u32_e32 v174, s46, v155
	ds_read_b128 v[140:143], v158
	ds_read_b128 v[144:147], v158 offset:1024
	ds_read_b128 v[148:151], v158 offset:2048
	ds_read_b128 v[158:161], v158 offset:3072
	ds_read_b128 v[162:165], v174
	ds_read_b128 v[166:169], v174 offset:1024
	ds_read_b128 v[170:173], v174 offset:2048
	ds_read_b128 v[174:177], v174 offset:3072
	s_add_u32 s22, s22, 0x40000
	s_addc_u32 s23, s23, 0
	s_mov_b32 m0, s27
	v_lshl_add_u64 v[216:217], s[22:23], 0, v[134:135]
	ds_read_b128 v[178:181], v157 offset:32768
	ds_read_b128 v[182:185], v157 offset:33792
	ds_read_b128 v[186:189], v157 offset:34816
	ds_read_b128 v[190:193], v157 offset:35840
	ds_read_b128 v[194:197], v157 offset:36864
	ds_read_b128 v[198:201], v157 offset:37888
	ds_read_b128 v[202:205], v157 offset:38912
	ds_read_b128 v[206:209], v157 offset:39936
	global_load_lds_dwordx4 v[216:217], off
	v_lshl_add_u64 v[216:217], s[22:23], 0, v[132:133]
	s_mov_b32 m0, s28
	s_nop 0
	global_load_lds_dwordx4 v[216:217], off
	s_waitcnt vmcnt(8)
	s_waitcnt lgkmcnt(0)
	s_setprio 1
	s_barrier
	s_waitcnt lgkmcnt(0)
	v_mfma_f32_16x16x32_bf16 v[126:129], v[140:143], v[178:181], v[126:129]
	v_mfma_f32_16x16x32_bf16 v[122:125], v[148:151], v[178:181], v[122:125]
	v_mfma_f32_16x16x32_bf16 v[118:121], v[140:143], v[186:189], v[118:121]
	v_mfma_f32_16x16x32_bf16 v[114:117], v[148:151], v[186:189], v[114:117]
	v_mfma_f32_16x16x32_bf16 v[98:101], v[140:143], v[194:197], v[98:101]
	v_mfma_f32_16x16x32_bf16 v[90:93], v[148:151], v[194:197], v[90:93]
	v_mfma_f32_16x16x32_bf16 v[78:81], v[140:143], v[202:205], v[78:81]
	v_mfma_f32_16x16x32_bf16 v[74:77], v[148:151], v[202:205], v[74:77]
	v_mfma_f32_16x16x32_bf16 v[126:129], v[144:147], v[182:185], v[126:129]
	v_mfma_f32_16x16x32_bf16 v[122:125], v[158:161], v[182:185], v[122:125]
	v_mfma_f32_16x16x32_bf16 v[118:121], v[144:147], v[190:193], v[118:121]
	v_mfma_f32_16x16x32_bf16 v[114:117], v[158:161], v[190:193], v[114:117]
	v_mfma_f32_16x16x32_bf16 v[98:101], v[144:147], v[198:201], v[98:101]
	v_mfma_f32_16x16x32_bf16 v[90:93], v[158:161], v[198:201], v[90:93]
	v_mfma_f32_16x16x32_bf16 v[78:81], v[144:147], v[206:209], v[78:81]
	v_mfma_f32_16x16x32_bf16 v[74:77], v[158:161], v[206:209], v[74:77]
	v_mfma_f32_16x16x32_bf16 v[110:113], v[162:165], v[178:181], v[110:113]
	v_mfma_f32_16x16x32_bf16 v[106:109], v[170:173], v[178:181], v[106:109]
	v_mfma_f32_16x16x32_bf16 v[102:105], v[162:165], v[186:189], v[102:105]
	v_mfma_f32_16x16x32_bf16 v[94:97], v[170:173], v[186:189], v[94:97]
	v_mfma_f32_16x16x32_bf16 v[86:89], v[162:165], v[194:197], v[86:89]
	v_mfma_f32_16x16x32_bf16 v[82:85], v[170:173], v[194:197], v[82:85]
	v_mfma_f32_16x16x32_bf16 v[70:73], v[162:165], v[202:205], v[70:73]
	v_mfma_f32_16x16x32_bf16 v[66:69], v[170:173], v[202:205], v[66:69]
	v_mfma_f32_16x16x32_bf16 v[110:113], v[166:169], v[182:185], v[110:113]
	v_mfma_f32_16x16x32_bf16 v[106:109], v[174:177], v[182:185], v[106:109]
	v_mfma_f32_16x16x32_bf16 v[102:105], v[166:169], v[190:193], v[102:105]
	v_mfma_f32_16x16x32_bf16 v[94:97], v[174:177], v[190:193], v[94:97]
	v_mfma_f32_16x16x32_bf16 v[86:89], v[166:169], v[198:201], v[86:89]
	v_mfma_f32_16x16x32_bf16 v[82:85], v[174:177], v[198:201], v[82:85]
	v_mfma_f32_16x16x32_bf16 v[70:73], v[166:169], v[206:209], v[70:73]
	v_mfma_f32_16x16x32_bf16 v[66:69], v[174:177], v[206:209], v[66:69]
	s_barrier
; #define PG8_STAGE(bufoff, gbase, voff) do { _Pragma("unroll") for (int _i = 0; _i < 2; ++_i) \
;         __builtin_amdgcn_global_load_lds((const unsigned*)((const char*)(gbase) + (voff)[_i]), (PG8_LAS unsigned*)(lds + (bufoff) + ldsw + _i * 8192), 16, 0, 0); } while (0)
; #define PG8_LDA(dst, b, h) do { _Pragma("unroll") for (int m = 0; m < 4; ++m) _Pragma("unroll") for (int k = 0; k < 2; ++k) dst[m][k] = *(const PG8_LAS bf16x8*)(lds + PG8_SA(b, h) + aoff + m * 2048 + k * 1024); } while (0)
; #define PG8_MMA(ai, bj, At, Bt) do { __builtin_amdgcn_s_setprio(1); _Pragma("unroll") for (int m = 0; m < 4; ++m) _Pragma("unroll") for (int n = 0; n < 2; ++n) _Pragma("unroll") for (int k = 0; k < 2; ++k) \
;         acc[ai][bj][m][n] = __builtin_amdgcn_mfma_f32_16x16x32_bf16(Bt[n][k], At[m][k], acc[ai][bj][m][n], 0, 0, 0); __builtin_amdgcn_s_setprio(0); } while (0)
; #define PG8_WAIT_V(n) asm volatile("s_waitcnt vmcnt(" #n ")" ::: "memory")
; #define PG8_WAIT_L(n) asm volatile("s_waitcnt lgkmcnt(" #n ")" ::: "memory")
; #define PG8_BAR __builtin_amdgcn_s_barrier()
; #define PG8_SCHED __builtin_amdgcn_sched_barrier(0)
; template <class Epi, class Sched, bool ALIGN_EPI = false, bool SP2 = false>
; __device__ __forceinline__ void gemm_phase(PG8_LAS unsigned char* lds, const Gemm g, const Sched& S, const Epi& E, const int wv) {
;     ...
;             PG8_LDA(At, 1, 1); PG8_STAGE(PG8_SB(1, 0), b3, voffB); PG8_STAGE(PG8_SB(1, 1), b3 + hstep, voffB); PG8_STAGE(PG8_SA(1, 0), a3, voffA);
;             PG8_WAIT_V(8); PG8_WAIT_L(0); PG8_BAR; PG8_MMA(1, 0, At, B0); PG8_MMA(1, 1, At, B1); PG8_BAR; PG8_SCHED;
	s_setprio 0
	s_add_i32 s22, s45, s24
	v_lshl_add_u64 v[152:153], v[152:153], 0, s[2:3]
	s_mov_b32 m0, s22
	ds_read_b128 v[178:181], v157 offset:49152
	ds_read_b128 v[182:185], v157 offset:50176
	ds_read_b128 v[186:189], v157 offset:51200
	ds_read_b128 v[190:193], v157 offset:52224
	ds_read_b128 v[194:197], v157 offset:53248
	ds_read_b128 v[198:201], v157 offset:54272
	ds_read_b128 v[202:205], v157 offset:55296
	ds_read_b128 v[206:209], v157 offset:56320
	global_load_lds_dwordx4 v[152:153], off
	s_add_i32 m0, s22, 0x2000
	s_add_u32 s20, s20, 0x40080
	v_lshl_add_u64 v[152:153], v[210:211], 0, s[2:3]
	s_addc_u32 s21, s21, 0
	s_add_i32 s22, s46, s24
	global_load_lds_dwordx4 v[152:153], off
	v_lshl_add_u64 v[152:153], s[20:21], 0, v[0:1]
	s_mov_b32 m0, s22
	s_nop 0
	global_load_lds_dwordx4 v[152:153], off
	v_lshl_add_u64 v[152:153], s[20:21], 0, v[130:131]
	s_add_i32 m0, s22, 0x2000
	s_nop 0
	global_load_lds_dwordx4 v[152:153], off
	v_lshl_add_u64 v[152:153], v[212:213], 0, s[2:3]
	s_mov_b32 m0, s33
	s_nop 0
	global_load_lds_dwordx4 v[152:153], off
	v_lshl_add_u64 v[152:153], v[214:215], 0, s[2:3]
	s_mov_b32 m0, s35
	s_nop 0
	global_load_lds_dwordx4 v[152:153], off
	s_waitcnt vmcnt(8)
	s_waitcnt lgkmcnt(0)
	s_setprio 1
	s_barrier
	s_waitcnt lgkmcnt(0)
	v_mfma_f32_16x16x32_bf16 v[62:65], v[140:143], v[178:181], v[62:65]
	v_mfma_f32_16x16x32_bf16 v[58:61], v[148:151], v[178:181], v[58:61]
	v_mfma_f32_16x16x32_bf16 v[46:49], v[140:143], v[186:189], v[46:49]
	v_mfma_f32_16x16x32_bf16 v[42:45], v[148:151], v[186:189], v[42:45]
	v_mfma_f32_16x16x32_bf16 v[30:33], v[140:143], v[194:197], v[30:33]
	v_mfma_f32_16x16x32_bf16 v[26:29], v[148:151], v[194:197], v[26:29]
	v_mfma_f32_16x16x32_bf16 v[14:17], v[140:143], v[202:205], v[14:17]
	v_mfma_f32_16x16x32_bf16 v[10:13], v[148:151], v[202:205], v[10:13]
	v_mfma_f32_16x16x32_bf16 v[62:65], v[144:147], v[182:185], v[62:65]
	v_mfma_f32_16x16x32_bf16 v[58:61], v[158:161], v[182:185], v[58:61]
	v_mfma_f32_16x16x32_bf16 v[46:49], v[144:147], v[190:193], v[46:49]
	v_mfma_f32_16x16x32_bf16 v[42:45], v[158:161], v[190:193], v[42:45]
	v_mfma_f32_16x16x32_bf16 v[30:33], v[144:147], v[198:201], v[30:33]
	v_mfma_f32_16x16x32_bf16 v[26:29], v[158:161], v[198:201], v[26:29]
	v_mfma_f32_16x16x32_bf16 v[14:17], v[144:147], v[206:209], v[14:17]
	v_mfma_f32_16x16x32_bf16 v[10:13], v[158:161], v[206:209], v[10:13]
	v_mfma_f32_16x16x32_bf16 v[54:57], v[162:165], v[178:181], v[54:57]
	v_mfma_f32_16x16x32_bf16 v[50:53], v[170:173], v[178:181], v[50:53]
	v_mfma_f32_16x16x32_bf16 v[38:41], v[162:165], v[186:189], v[38:41]
	v_mfma_f32_16x16x32_bf16 v[34:37], v[170:173], v[186:189], v[34:37]
	v_mfma_f32_16x16x32_bf16 v[22:25], v[162:165], v[194:197], v[22:25]
	v_mfma_f32_16x16x32_bf16 v[18:21], v[170:173], v[194:197], v[18:21]
	v_mfma_f32_16x16x32_bf16 v[6:9], v[162:165], v[202:205], v[6:9]
	v_mfma_f32_16x16x32_bf16 v[2:5], v[170:173], v[202:205], v[2:5]
	v_mfma_f32_16x16x32_bf16 v[54:57], v[166:169], v[182:185], v[54:57]
	v_mfma_f32_16x16x32_bf16 v[50:53], v[174:177], v[182:185], v[50:53]
	v_mfma_f32_16x16x32_bf16 v[38:41], v[166:169], v[190:193], v[38:41]
	v_mfma_f32_16x16x32_bf16 v[34:37], v[174:177], v[190:193], v[34:37]
	v_mfma_f32_16x16x32_bf16 v[22:25], v[166:169], v[198:201], v[22:25]
	v_mfma_f32_16x16x32_bf16 v[18:21], v[174:177], v[198:201], v[18:21]
	v_mfma_f32_16x16x32_bf16 v[6:9], v[166:169], v[206:209], v[6:9]
	v_mfma_f32_16x16x32_bf16 v[2:5], v[174:177], v[206:209], v[2:5]
	s_barrier
	s_setprio 0
	s_add_i32 s44, s44, 2
	s_add_u32 s18, s18, 0x100
	s_addc_u32 s19, s19, 0
	s_add_u32 s42, s42, 0x100
	s_addc_u32 s43, s43, 0
	s_cmp_gt_u32 s44, 13
	s_cbranch_scc0 .LBB0_156
	s_and_b64 vcc, exec, s[6:7]
	s_cbranch_vccz .LBB0_159
	s_barrier

; #define PG8_STAGE(bufoff, gbase, voff) do { _Pragma("unroll") for (int _i = 0; _i < 2; ++_i) \
;         __builtin_amdgcn_global_load_lds((const unsigned*)((const char*)(gbase) + (voff)[_i]), (PG8_LAS unsigned*)(lds + (bufoff) + ldsw + _i * 8192), 16, 0, 0); } while (0)
; #define PG8_LDA(dst, b, h) do { _Pragma("unroll") for (int m = 0; m < 4; ++m) _Pragma("unroll") for (int k = 0; k < 2; ++k) dst[m][k] = *(const PG8_LAS bf16x8*)(lds + PG8_SA(b, h) + aoff + m * 2048 + k * 1024); } while (0)
; #define PG8_LDB(dst, b, h) do { _Pragma("unroll") for (int n = 0; n < 2; ++n) _Pragma("unroll") for (int k = 0; k < 2; ++k) dst[n][k] = *(const PG8_LAS bf16x8*)(lds + PG8_SB(b, h) + boff + n * 2048 + k * 1024); } while (0)
; #define PG8_MMA(ai, bj, At, Bt) do { __builtin_amdgcn_s_setprio(1); _Pragma("unroll") for (int m = 0; m < 4; ++m) _Pragma("unroll") for (int n = 0; n < 2; ++n) _Pragma("unroll") for (int k = 0; k < 2; ++k) \
;         acc[ai][bj][m][n] = __builtin_amdgcn_mfma_f32_16x16x32_bf16(Bt[n][k], At[m][k], acc[ai][bj][m][n], 0, 0, 0); __builtin_amdgcn_s_setprio(0); } while (0)
; #define PG8_WAIT_V(n) asm volatile("s_waitcnt vmcnt(" #n ")" ::: "memory")
; #define PG8_WAIT_L(n) asm volatile("s_waitcnt lgkmcnt(" #n ")" ::: "memory")
; #define PG8_BAR __builtin_amdgcn_s_barrier()
; #define PG8_SCHED __builtin_amdgcn_sched_barrier(0)
; template <class Epi, class Sched, bool ALIGN_EPI = false, bool SP2 = false>
; __device__ __forceinline__ void gemm_phase(PG8_LAS unsigned char* lds, const Gemm g, const Sched& S, const Epi& E, const int wv) {
;     ...
;             const bool last = (t == nt - 2);
;             const char* a1 = cA + (size_t)(t + 1) * kstep;
;             const char* a2 = last ? nA : cA + (size_t)(t + 2) * kstep; const char* b2 = last ? nB : cB + (size_t)(t + 2) * kstep;
;             const char* a3 = a2 + kstep; const char* b3 = b2 + kstep;
;             if (last && has_next) S.a_ready(nxt);
;             if constexpr (SP2) {
;             PG8_LDB(B0, 0, 0); PG8_LDB(B1, 0, 1); PG8_SCHED; PG8_LDA(At, 0, 0); PG8_STAGE(PG8_SA(1, 1), a1 + hstep, voffA);
;             PG8_WAIT_V(8); PG8_WAIT_L(0); PG8_BAR; PG8_MMA(0, 0, At, B0); PG8_MMA(0, 1, At, B1); PG8_BAR; PG8_SCHED;
;             PG8_LDA(At, 0, 1); PG8_STAGE(PG8_SB(0, 0), b2, voffB); PG8_STAGE(PG8_SB(0, 1), b2 + hstep, voffB); PG8_STAGE(PG8_SA(0, 0), a2, voffA);
.LBB0_350:
	s_add_u32 s24, s22, 0xfffc0080
	s_addc_u32 s25, s23, -1
	s_add_i32 s48, 0, 0x10000
	s_cmp_eq_u32 s47, 12
	s_cselect_b32 s27, s13, s25
	s_cselect_b32 s26, s19, s24
	s_cselect_b32 s25, s11, s46
	s_cselect_b32 s24, s33, s45
	s_add_i32 s50, 0, 0x14000
	v_add_u32_e32 v126, s48, v183
	v_add_u32_e32 v168, s50, v183
	ds_read_b128 v[114:117], v126
	ds_read_b128 v[118:121], v126 offset:1024
	ds_read_b128 v[122:125], v126 offset:2048
	ds_read_b128 v[126:129], v126 offset:3072
	ds_read_b128 v[130:133], v168
	ds_read_b128 v[134:137], v168 offset:1024
	ds_read_b128 v[164:167], v168 offset:2048
	ds_read_b128 v[168:171], v168 offset:3072
	v_lshl_add_u64 v[180:181], s[22:23], 0, v[160:161]
	s_add_i32 m0, s21, 0xc000
	ds_read_b128 v[172:175], v185
	ds_read_b128 v[176:179], v185 offset:1024
	ds_read_b128 v[186:189], v185 offset:2048
	ds_read_b128 v[190:193], v185 offset:3072
	ds_read_b128 v[194:197], v185 offset:4096
	ds_read_b128 v[198:201], v185 offset:5120
	ds_read_b128 v[202:205], v185 offset:6144
	ds_read_b128 v[206:209], v185 offset:7168
	global_load_lds_dwordx4 v[180:181], off
	v_lshl_add_u64 v[180:181], s[22:23], 0, v[162:163]
	s_add_i32 m0, s21, 0xe000
	s_nop 0
	global_load_lds_dwordx4 v[180:181], off
	s_waitcnt vmcnt(8)
	s_waitcnt lgkmcnt(0)
	s_setprio 1
	s_barrier
	s_waitcnt lgkmcnt(0)
	v_mfma_f32_16x16x32_bf16 v[150:153], v[114:117], v[172:175], v[150:153]
	v_mfma_f32_16x16x32_bf16 v[146:149], v[122:125], v[172:175], v[146:149]
	v_mfma_f32_16x16x32_bf16 v[110:113], v[114:117], v[186:189], v[110:113]
	v_mfma_f32_16x16x32_bf16 v[106:109], v[122:125], v[186:189], v[106:109]
	v_mfma_f32_16x16x32_bf16 v[94:97], v[114:117], v[194:197], v[94:97]
	v_mfma_f32_16x16x32_bf16 v[90:93], v[122:125], v[194:197], v[90:93]
	v_mfma_f32_16x16x32_bf16 v[78:81], v[114:117], v[202:205], v[78:81]
	v_mfma_f32_16x16x32_bf16 v[74:77], v[122:125], v[202:205], v[74:77]
	v_mfma_f32_16x16x32_bf16 v[150:153], v[118:121], v[176:179], v[150:153]
	v_mfma_f32_16x16x32_bf16 v[146:149], v[126:129], v[176:179], v[146:149]
	v_mfma_f32_16x16x32_bf16 v[110:113], v[118:121], v[190:193], v[110:113]
	v_mfma_f32_16x16x32_bf16 v[106:109], v[126:129], v[190:193], v[106:109]
	v_mfma_f32_16x16x32_bf16 v[94:97], v[118:121], v[198:201], v[94:97]
	v_mfma_f32_16x16x32_bf16 v[90:93], v[126:129], v[198:201], v[90:93]
	v_mfma_f32_16x16x32_bf16 v[78:81], v[118:121], v[206:209], v[78:81]
	v_mfma_f32_16x16x32_bf16 v[74:77], v[126:129], v[206:209], v[74:77]
	v_mfma_f32_16x16x32_bf16 v[142:145], v[130:133], v[172:175], v[142:145]
	v_mfma_f32_16x16x32_bf16 v[138:141], v[164:167], v[172:175], v[138:141]
	v_mfma_f32_16x16x32_bf16 v[102:105], v[130:133], v[186:189], v[102:105]
	v_mfma_f32_16x16x32_bf16 v[98:101], v[164:167], v[186:189], v[98:101]
	v_mfma_f32_16x16x32_bf16 v[86:89], v[130:133], v[194:197], v[86:89]
	v_mfma_f32_16x16x32_bf16 v[82:85], v[164:167], v[194:197], v[82:85]
	v_mfma_f32_16x16x32_bf16 v[70:73], v[130:133], v[202:205], v[70:73]
	v_mfma_f32_16x16x32_bf16 v[66:69], v[164:167], v[202:205], v[66:69]
	v_mfma_f32_16x16x32_bf16 v[142:145], v[134:137], v[176:179], v[142:145]
	v_mfma_f32_16x16x32_bf16 v[138:141], v[168:171], v[176:179], v[138:141]
	v_mfma_f32_16x16x32_bf16 v[102:105], v[134:137], v[190:193], v[102:105]
	v_mfma_f32_16x16x32_bf16 v[98:101], v[168:171], v[190:193], v[98:101]
	v_mfma_f32_16x16x32_bf16 v[86:89], v[134:137], v[198:201], v[86:89]
	v_mfma_f32_16x16x32_bf16 v[82:85], v[168:171], v[198:201], v[82:85]
	v_mfma_f32_16x16x32_bf16 v[70:73], v[134:137], v[206:209], v[70:73]
	v_mfma_f32_16x16x32_bf16 v[66:69], v[168:171], v[206:209], v[66:69]
	s_barrier
	s_setprio 0
	s_add_i32 s48, s48, s36
	v_lshl_add_u64 v[180:181], s[24:25], 0, v[0:1]
	s_mov_b32 m0, s48
	ds_read_b128 v[172:175], v185 offset:16384
	ds_read_b128 v[176:179], v185 offset:17408
	ds_read_b128 v[186:189], v185 offset:18432
	ds_read_b128 v[190:193], v185 offset:19456
	ds_read_b128 v[194:197], v185 offset:20480
	ds_read_b128 v[198:201], v185 offset:21504
	ds_read_b128 v[202:205], v185 offset:22528
	ds_read_b128 v[206:209], v185 offset:23552
	global_load_lds_dwordx4 v[180:181], off
	s_add_i32 m0, s48, 0x2000
	s_add_u32 s48, s24, 0x40000
	v_lshl_add_u64 v[210:211], s[24:25], 0, v[158:159]
	s_addc_u32 s49, s25, 0
	s_add_i32 s50, s50, s36
	global_load_lds_dwordx4 v[210:211], off
	v_lshl_add_u64 v[212:213], s[48:49], 0, v[0:1]
	s_mov_b32 m0, s50
	v_lshl_add_u64 v[214:215], s[26:27], 0, v[156:157]
	global_load_lds_dwordx4 v[212:213], off
	v_lshl_add_u64 v[212:213], s[48:49], 0, v[158:159]
	s_add_i32 m0, s50, 0x2000
	s_nop 0
	global_load_lds_dwordx4 v[212:213], off
	v_lshl_add_u64 v[212:213], s[26:27], 0, v[154:155]
	s_mov_b32 m0, s21
	s_nop 0
	global_load_lds_dwordx4 v[212:213], off
	s_mov_b32 m0, s37
	s_nop 0
	global_load_lds_dwordx4 v[214:215], off
	s_waitcnt vmcnt(8)
	s_waitcnt lgkmcnt(0)
	s_setprio 1
	s_barrier
; #define PG8_STAGE(bufoff, gbase, voff) do { _Pragma("unroll") for (int _i = 0; _i < 2; ++_i) \
;         __builtin_amdgcn_global_load_lds((const unsigned*)((const char*)(gbase) + (voff)[_i]), (PG8_LAS unsigned*)(lds + (bufoff) + ldsw + _i * 8192), 16, 0, 0); } while (0)
; #define PG8_LDA(dst, b, h) do { _Pragma("unroll") for (int m = 0; m < 4; ++m) _Pragma("unroll") for (int k = 0; k < 2; ++k) dst[m][k] = *(const PG8_LAS bf16x8*)(lds + PG8_SA(b, h) + aoff + m * 2048 + k * 1024); } while (0)
; #define PG8_LDB(dst, b, h) do { _Pragma("unroll") for (int n = 0; n < 2; ++n) _Pragma("unroll") for (int k = 0; k < 2; ++k) dst[n][k] = *(const PG8_LAS bf16x8*)(lds + PG8_SB(b, h) + boff + n * 2048 + k * 1024); } while (0)
; #define PG8_MMA(ai, bj, At, Bt) do { __builtin_amdgcn_s_setprio(1); _Pragma("unroll") for (int m = 0; m < 4; ++m) _Pragma("unroll") for (int n = 0; n < 2; ++n) _Pragma("unroll") for (int k = 0; k < 2; ++k) \
;         acc[ai][bj][m][n] = __builtin_amdgcn_mfma_f32_16x16x32_bf16(Bt[n][k], At[m][k], acc[ai][bj][m][n], 0, 0, 0); __builtin_amdgcn_s_setprio(0); } while (0)
; #define PG8_WAIT_V(n) asm volatile("s_waitcnt vmcnt(" #n ")" ::: "memory")
; #define PG8_WAIT_L(n) asm volatile("s_waitcnt lgkmcnt(" #n ")" ::: "memory")
; #define PG8_BAR __builtin_amdgcn_s_barrier()
; #define PG8_SCHED __builtin_amdgcn_sched_barrier(0)
; template <class Epi, class Sched, bool ALIGN_EPI = false, bool SP2 = false>
; __device__ __forceinline__ void gemm_phase(PG8_LAS unsigned char* lds, const Gemm g, const Sched& S, const Epi& E, const int wv) {
;     ...
;             PG8_WAIT_V(8); PG8_WAIT_L(0); PG8_BAR; PG8_MMA(1, 0, At, B0); PG8_MMA(1, 1, At, B1); PG8_BAR; PG8_SCHED;
;             PG8_LDB(B0, 1, 0); PG8_LDB(B1, 1, 1); PG8_SCHED; PG8_LDA(At, 1, 0); PG8_STAGE(PG8_SA(0, 1), a2 + hstep, voffA);
;             PG8_WAIT_V(8); PG8_WAIT_L(0); PG8_BAR; PG8_MMA(0, 0, At, B0); PG8_MMA(0, 1, At, B1); PG8_BAR; PG8_SCHED;
	s_waitcnt lgkmcnt(0)
	v_mfma_f32_16x16x32_bf16 v[62:65], v[114:117], v[172:175], v[62:65]
	v_mfma_f32_16x16x32_bf16 v[58:61], v[122:125], v[172:175], v[58:61]
	v_mfma_f32_16x16x32_bf16 v[46:49], v[114:117], v[186:189], v[46:49]
	v_mfma_f32_16x16x32_bf16 v[42:45], v[122:125], v[186:189], v[42:45]
	v_mfma_f32_16x16x32_bf16 v[30:33], v[114:117], v[194:197], v[30:33]
	v_mfma_f32_16x16x32_bf16 v[26:29], v[122:125], v[194:197], v[26:29]
	v_mfma_f32_16x16x32_bf16 v[14:17], v[114:117], v[202:205], v[14:17]
	v_mfma_f32_16x16x32_bf16 v[10:13], v[122:125], v[202:205], v[10:13]
	v_mfma_f32_16x16x32_bf16 v[62:65], v[118:121], v[176:179], v[62:65]
	v_mfma_f32_16x16x32_bf16 v[58:61], v[126:129], v[176:179], v[58:61]
	v_mfma_f32_16x16x32_bf16 v[46:49], v[118:121], v[190:193], v[46:49]
	v_mfma_f32_16x16x32_bf16 v[42:45], v[126:129], v[190:193], v[42:45]
	v_mfma_f32_16x16x32_bf16 v[30:33], v[118:121], v[198:201], v[30:33]
	v_mfma_f32_16x16x32_bf16 v[26:29], v[126:129], v[198:201], v[26:29]
	v_mfma_f32_16x16x32_bf16 v[14:17], v[118:121], v[206:209], v[14:17]
	v_mfma_f32_16x16x32_bf16 v[10:13], v[126:129], v[206:209], v[10:13]
	v_mfma_f32_16x16x32_bf16 v[54:57], v[130:133], v[172:175], v[54:57]
	v_mfma_f32_16x16x32_bf16 v[50:53], v[164:167], v[172:175], v[50:53]
	v_mfma_f32_16x16x32_bf16 v[38:41], v[130:133], v[186:189], v[38:41]
	v_mfma_f32_16x16x32_bf16 v[34:37], v[164:167], v[186:189], v[34:37]
	v_mfma_f32_16x16x32_bf16 v[22:25], v[130:133], v[194:197], v[22:25]
	v_mfma_f32_16x16x32_bf16 v[18:21], v[164:167], v[194:197], v[18:21]
	v_mfma_f32_16x16x32_bf16 v[6:9], v[130:133], v[202:205], v[6:9]
	v_mfma_f32_16x16x32_bf16 v[2:5], v[164:167], v[202:205], v[2:5]
	v_mfma_f32_16x16x32_bf16 v[54:57], v[134:137], v[176:179], v[54:57]
	v_mfma_f32_16x16x32_bf16 v[50:53], v[168:171], v[176:179], v[50:53]
	v_mfma_f32_16x16x32_bf16 v[38:41], v[134:137], v[190:193], v[38:41]
	v_mfma_f32_16x16x32_bf16 v[34:37], v[168:171], v[190:193], v[34:37]
	v_mfma_f32_16x16x32_bf16 v[22:25], v[134:137], v[198:201], v[22:25]
	v_mfma_f32_16x16x32_bf16 v[18:21], v[168:171], v[198:201], v[18:21]
	v_mfma_f32_16x16x32_bf16 v[6:9], v[134:137], v[206:209], v[6:9]
	v_mfma_f32_16x16x32_bf16 v[2:5], v[168:171], v[206:209], v[2:5]
	s_barrier
	s_setprio 0
	s_add_i32 s48, 0, 0x18000
	s_add_i32 s49, 0, 0x1c000
	v_add_u32_e32 v126, s48, v183
	v_add_u32_e32 v168, s49, v183
	ds_read_b128 v[114:117], v126
	ds_read_b128 v[118:121], v126 offset:1024
	ds_read_b128 v[122:125], v126 offset:2048
	ds_read_b128 v[126:129], v126 offset:3072
	ds_read_b128 v[130:133], v168
	ds_read_b128 v[134:137], v168 offset:1024
	ds_read_b128 v[164:167], v168 offset:2048
	ds_read_b128 v[168:171], v168 offset:3072
	s_add_u32 s26, s26, 0x40000
	s_addc_u32 s27, s27, 0
	s_mov_b32 m0, s38
	v_lshl_add_u64 v[216:217], s[26:27], 0, v[154:155]
	ds_read_b128 v[172:175], v185 offset:32768
	ds_read_b128 v[176:179], v185 offset:33792
	ds_read_b128 v[186:189], v185 offset:34816
	ds_read_b128 v[190:193], v185 offset:35840
	ds_read_b128 v[194:197], v185 offset:36864
	ds_read_b128 v[198:201], v185 offset:37888
	ds_read_b128 v[202:205], v185 offset:38912
	ds_read_b128 v[206:209], v185 offset:39936
	global_load_lds_dwordx4 v[216:217], off
	v_lshl_add_u64 v[216:217], s[26:27], 0, v[156:157]
	s_mov_b32 m0, s39
	s_nop 0
	global_load_lds_dwordx4 v[216:217], off
	s_waitcnt vmcnt(8)
	s_waitcnt lgkmcnt(0)
	s_setprio 1
	s_barrier
	s_waitcnt lgkmcnt(0)
	v_mfma_f32_16x16x32_bf16 v[150:153], v[114:117], v[172:175], v[150:153]
	v_mfma_f32_16x16x32_bf16 v[146:149], v[122:125], v[172:175], v[146:149]
	v_mfma_f32_16x16x32_bf16 v[110:113], v[114:117], v[186:189], v[110:113]
	v_mfma_f32_16x16x32_bf16 v[106:109], v[122:125], v[186:189], v[106:109]
	v_mfma_f32_16x16x32_bf16 v[94:97], v[114:117], v[194:197], v[94:97]
	v_mfma_f32_16x16x32_bf16 v[90:93], v[122:125], v[194:197], v[90:93]
	v_mfma_f32_16x16x32_bf16 v[78:81], v[114:117], v[202:205], v[78:81]
	v_mfma_f32_16x16x32_bf16 v[74:77], v[122:125], v[202:205], v[74:77]
	v_mfma_f32_16x16x32_bf16 v[150:153], v[118:121], v[176:179], v[150:153]
	v_mfma_f32_16x16x32_bf16 v[146:149], v[126:129], v[176:179], v[146:149]
	v_mfma_f32_16x16x32_bf16 v[110:113], v[118:121], v[190:193], v[110:113]
	v_mfma_f32_16x16x32_bf16 v[106:109], v[126:129], v[190:193], v[106:109]
	v_mfma_f32_16x16x32_bf16 v[94:97], v[118:121], v[198:201], v[94:97]
	v_mfma_f32_16x16x32_bf16 v[90:93], v[126:129], v[198:201], v[90:93]
	v_mfma_f32_16x16x32_bf16 v[78:81], v[118:121], v[206:209], v[78:81]
	v_mfma_f32_16x16x32_bf16 v[74:77], v[126:129], v[206:209], v[74:77]
	v_mfma_f32_16x16x32_bf16 v[142:145], v[130:133], v[172:175], v[142:145]
	v_mfma_f32_16x16x32_bf16 v[138:141], v[164:167], v[172:175], v[138:141]
	v_mfma_f32_16x16x32_bf16 v[102:105], v[130:133], v[186:189], v[102:105]
	v_mfma_f32_16x16x32_bf16 v[98:101], v[164:167], v[186:189], v[98:101]
	v_mfma_f32_16x16x32_bf16 v[86:89], v[130:133], v[194:197], v[86:89]
	v_mfma_f32_16x16x32_bf16 v[82:85], v[164:167], v[194:197], v[82:85]
	v_mfma_f32_16x16x32_bf16 v[70:73], v[130:133], v[202:205], v[70:73]
	v_mfma_f32_16x16x32_bf16 v[66:69], v[164:167], v[202:205], v[66:69]
	v_mfma_f32_16x16x32_bf16 v[142:145], v[134:137], v[176:179], v[142:145]
	v_mfma_f32_16x16x32_bf16 v[138:141], v[168:171], v[176:179], v[138:141]
	v_mfma_f32_16x16x32_bf16 v[102:105], v[134:137], v[190:193], v[102:105]
	v_mfma_f32_16x16x32_bf16 v[98:101], v[168:171], v[190:193], v[98:101]
	v_mfma_f32_16x16x32_bf16 v[86:89], v[134:137], v[198:201], v[86:89]
	v_mfma_f32_16x16x32_bf16 v[82:85], v[168:171], v[198:201], v[82:85]
	v_mfma_f32_16x16x32_bf16 v[70:73], v[134:137], v[206:209], v[70:73]
	v_mfma_f32_16x16x32_bf16 v[66:69], v[168:171], v[206:209], v[66:69]
	s_barrier
; #define PG8_STAGE(bufoff, gbase, voff) do { _Pragma("unroll") for (int _i = 0; _i < 2; ++_i) \
;         __builtin_amdgcn_global_load_lds((const unsigned*)((const char*)(gbase) + (voff)[_i]), (PG8_LAS unsigned*)(lds + (bufoff) + ldsw + _i * 8192), 16, 0, 0); } while (0)
; #define PG8_LDA(dst, b, h) do { _Pragma("unroll") for (int m = 0; m < 4; ++m) _Pragma("unroll") for (int k = 0; k < 2; ++k) dst[m][k] = *(const PG8_LAS bf16x8*)(lds + PG8_SA(b, h) + aoff + m * 2048 + k * 1024); } while (0)
; #define PG8_MMA(ai, bj, At, Bt) do { __builtin_amdgcn_s_setprio(1); _Pragma("unroll") for (int m = 0; m < 4; ++m) _Pragma("unroll") for (int n = 0; n < 2; ++n) _Pragma("unroll") for (int k = 0; k < 2; ++k) \
;         acc[ai][bj][m][n] = __builtin_amdgcn_mfma_f32_16x16x32_bf16(Bt[n][k], At[m][k], acc[ai][bj][m][n], 0, 0, 0); __builtin_amdgcn_s_setprio(0); } while (0)
; #define PG8_WAIT_V(n) asm volatile("s_waitcnt vmcnt(" #n ")" ::: "memory")
; #define PG8_WAIT_L(n) asm volatile("s_waitcnt lgkmcnt(" #n ")" ::: "memory")
; #define PG8_BAR __builtin_amdgcn_s_barrier()
; #define PG8_SCHED __builtin_amdgcn_sched_barrier(0)
; template <class Epi, class Sched, bool ALIGN_EPI = false, bool SP2 = false>
; __device__ __forceinline__ void gemm_phase(PG8_LAS unsigned char* lds, const Gemm g, const Sched& S, const Epi& E, const int wv) {
;     ...
;             PG8_LDA(At, 1, 1); PG8_STAGE(PG8_SB(1, 0), b3, voffB); PG8_STAGE(PG8_SB(1, 1), b3 + hstep, voffB); PG8_STAGE(PG8_SA(1, 0), a3, voffA);
;             PG8_WAIT_V(8); PG8_WAIT_L(0); PG8_BAR; PG8_MMA(1, 0, At, B0); PG8_MMA(1, 1, At, B1); PG8_BAR; PG8_SCHED;
	s_setprio 0
	s_add_i32 s26, s48, s36
	v_lshl_add_u64 v[180:181], v[180:181], 0, s[2:3]
	s_mov_b32 m0, s26
	ds_read_b128 v[172:175], v185 offset:49152
	ds_read_b128 v[176:179], v185 offset:50176
	ds_read_b128 v[186:189], v185 offset:51200
	ds_read_b128 v[190:193], v185 offset:52224
	ds_read_b128 v[194:197], v185 offset:53248
	ds_read_b128 v[198:201], v185 offset:54272
	ds_read_b128 v[202:205], v185 offset:55296
	ds_read_b128 v[206:209], v185 offset:56320
	global_load_lds_dwordx4 v[180:181], off
	s_add_i32 m0, s26, 0x2000
	s_add_u32 s24, s24, 0x40080
	v_lshl_add_u64 v[180:181], v[210:211], 0, s[2:3]
	s_addc_u32 s25, s25, 0
	s_add_i32 s26, s49, s36
	global_load_lds_dwordx4 v[180:181], off
	v_lshl_add_u64 v[180:181], s[24:25], 0, v[0:1]
	s_mov_b32 m0, s26
	s_nop 0
	global_load_lds_dwordx4 v[180:181], off
	v_lshl_add_u64 v[180:181], s[24:25], 0, v[158:159]
	s_add_i32 m0, s26, 0x2000
	s_nop 0
	global_load_lds_dwordx4 v[180:181], off
	v_lshl_add_u64 v[180:181], v[212:213], 0, s[2:3]
	s_mov_b32 m0, s40
	s_nop 0
	global_load_lds_dwordx4 v[180:181], off
	v_lshl_add_u64 v[180:181], v[214:215], 0, s[2:3]
	s_mov_b32 m0, s41
	s_nop 0
	global_load_lds_dwordx4 v[180:181], off
	s_waitcnt vmcnt(8)
	s_waitcnt lgkmcnt(0)
	s_setprio 1
	s_barrier
	s_waitcnt lgkmcnt(0)
	v_mfma_f32_16x16x32_bf16 v[62:65], v[114:117], v[172:175], v[62:65]
	v_mfma_f32_16x16x32_bf16 v[58:61], v[122:125], v[172:175], v[58:61]
	v_mfma_f32_16x16x32_bf16 v[46:49], v[114:117], v[186:189], v[46:49]
	v_mfma_f32_16x16x32_bf16 v[42:45], v[122:125], v[186:189], v[42:45]
	v_mfma_f32_16x16x32_bf16 v[30:33], v[114:117], v[194:197], v[30:33]
	v_mfma_f32_16x16x32_bf16 v[26:29], v[122:125], v[194:197], v[26:29]
	v_mfma_f32_16x16x32_bf16 v[14:17], v[114:117], v[202:205], v[14:17]
	v_mfma_f32_16x16x32_bf16 v[10:13], v[122:125], v[202:205], v[10:13]
	v_mfma_f32_16x16x32_bf16 v[62:65], v[118:121], v[176:179], v[62:65]
	v_mfma_f32_16x16x32_bf16 v[58:61], v[126:129], v[176:179], v[58:61]
	v_mfma_f32_16x16x32_bf16 v[46:49], v[118:121], v[190:193], v[46:49]
	v_mfma_f32_16x16x32_bf16 v[42:45], v[126:129], v[190:193], v[42:45]
	v_mfma_f32_16x16x32_bf16 v[30:33], v[118:121], v[198:201], v[30:33]
	v_mfma_f32_16x16x32_bf16 v[26:29], v[126:129], v[198:201], v[26:29]
	v_mfma_f32_16x16x32_bf16 v[14:17], v[118:121], v[206:209], v[14:17]
	v_mfma_f32_16x16x32_bf16 v[10:13], v[126:129], v[206:209], v[10:13]
	v_mfma_f32_16x16x32_bf16 v[54:57], v[130:133], v[172:175], v[54:57]
	v_mfma_f32_16x16x32_bf16 v[50:53], v[164:167], v[172:175], v[50:53]
	v_mfma_f32_16x16x32_bf16 v[38:41], v[130:133], v[186:189], v[38:41]
	v_mfma_f32_16x16x32_bf16 v[34:37], v[164:167], v[186:189], v[34:37]
	v_mfma_f32_16x16x32_bf16 v[22:25], v[130:133], v[194:197], v[22:25]
	v_mfma_f32_16x16x32_bf16 v[18:21], v[164:167], v[194:197], v[18:21]
	v_mfma_f32_16x16x32_bf16 v[6:9], v[130:133], v[202:205], v[6:9]
	v_mfma_f32_16x16x32_bf16 v[2:5], v[164:167], v[202:205], v[2:5]
	v_mfma_f32_16x16x32_bf16 v[54:57], v[134:137], v[176:179], v[54:57]
	v_mfma_f32_16x16x32_bf16 v[50:53], v[168:171], v[176:179], v[50:53]
	v_mfma_f32_16x16x32_bf16 v[38:41], v[134:137], v[190:193], v[38:41]
	v_mfma_f32_16x16x32_bf16 v[34:37], v[168:171], v[190:193], v[34:37]
	v_mfma_f32_16x16x32_bf16 v[22:25], v[134:137], v[198:201], v[22:25]
	v_mfma_f32_16x16x32_bf16 v[18:21], v[168:171], v[198:201], v[18:21]
	v_mfma_f32_16x16x32_bf16 v[6:9], v[134:137], v[206:209], v[6:9]
	v_mfma_f32_16x16x32_bf16 v[2:5], v[168:171], v[206:209], v[2:5]
	s_barrier
	s_setprio 0
	s_add_i32 s47, s47, 2
	s_add_u32 s22, s22, 0x100
	s_addc_u32 s23, s23, 0
	s_add_u32 s45, s45, 0x100
	s_addc_u32 s46, s46, 0
	s_cmp_gt_u32 s47, 13
	s_cbranch_scc0 .LBB0_350
	s_and_b64 vcc, exec, s[8:9]
	s_cbranch_vccz .LBB0_353
	s_barrier

; #define PG8_STAGE(bufoff, gbase, voff) do { _Pragma("unroll") for (int _i = 0; _i < 2; ++_i) \
;         __builtin_amdgcn_global_load_lds((const unsigned*)((const char*)(gbase) + (voff)[_i]), (PG8_LAS unsigned*)(lds + (bufoff) + ldsw + _i * 8192), 16, 0, 0); } while (0)
; #define PG8_LDA(dst, b, h) do { _Pragma("unroll") for (int m = 0; m < 4; ++m) _Pragma("unroll") for (int k = 0; k < 2; ++k) dst[m][k] = *(const PG8_LAS bf16x8*)(lds + PG8_SA(b, h) + aoff + m * 2048 + k * 1024); } while (0)
; #define PG8_LDB(dst, b, h) do { _Pragma("unroll") for (int n = 0; n < 2; ++n) _Pragma("unroll") for (int k = 0; k < 2; ++k) dst[n][k] = *(const PG8_LAS bf16x8*)(lds + PG8_SB(b, h) + boff + n * 2048 + k * 1024); } while (0)
; #define PG8_MMA(ai, bj, At, Bt) do { __builtin_amdgcn_s_setprio(1); _Pragma("unroll") for (int m = 0; m < 4; ++m) _Pragma("unroll") for (int n = 0; n < 2; ++n) _Pragma("unroll") for (int k = 0; k < 2; ++k) \
;         acc[ai][bj][m][n] = __builtin_amdgcn_mfma_f32_16x16x32_bf16(Bt[n][k], At[m][k], acc[ai][bj][m][n], 0, 0, 0); __builtin_amdgcn_s_setprio(0); } while (0)
; #define PG8_WAIT_V(n) asm volatile("s_waitcnt vmcnt(" #n ")" ::: "memory")
; #define PG8_WAIT_L(n) asm volatile("s_waitcnt lgkmcnt(" #n ")" ::: "memory")
; #define PG8_BAR __builtin_amdgcn_s_barrier()
; #define PG8_SCHED __builtin_amdgcn_sched_barrier(0)
; template <class Epi, class Sched, bool ALIGN_EPI = false, bool SP2 = false>
; __device__ __forceinline__ void gemm_phase(PG8_LAS unsigned char* lds, const Gemm g, const Sched& S, const Epi& E, const int wv) {
;     ...
;             const bool last = (t == nt - 2);
;             const char* a1 = cA + (size_t)(t + 1) * kstep;
;             const char* a2 = last ? nA : cA + (size_t)(t + 2) * kstep; const char* b2 = last ? nB : cB + (size_t)(t + 2) * kstep;
;             const char* a3 = a2 + kstep; const char* b3 = b2 + kstep;
;             if (last && has_next) S.a_ready(nxt);
;             if constexpr (SP2) {
;             PG8_LDB(B0, 0, 0); PG8_LDB(B1, 0, 1); PG8_SCHED; PG8_LDA(At, 0, 0); PG8_STAGE(PG8_SA(1, 1), a1 + hstep, voffA);
;             PG8_WAIT_V(8); PG8_WAIT_L(0); PG8_BAR; PG8_MMA(0, 0, At, B0); PG8_MMA(0, 1, At, B1); PG8_BAR; PG8_SCHED;
;             PG8_LDA(At, 0, 1); PG8_STAGE(PG8_SB(0, 0), b2, voffB); PG8_STAGE(PG8_SB(0, 1), b2 + hstep, voffB); PG8_STAGE(PG8_SA(0, 0), a2, voffA);
.LBB0_428:
	s_add_u32 s20, s18, 0xfffc0080
	s_addc_u32 s21, s19, -1
	s_add_i32 s46, 0, 0x10000
	s_cmp_eq_u32 s45, 12
	s_cselect_b32 s23, s11, s21
	s_cselect_b32 s22, s33, s20
	s_cselect_b32 s21, s9, s44
	s_cselect_b32 s20, s42, s43
	s_add_i32 s48, 0, 0x14000
	v_add_u32_e32 v152, s46, v166
	v_add_u32_e32 v164, s48, v166
	ds_read_b128 v[140:143], v152
	ds_read_b128 v[144:147], v152 offset:1024
	ds_read_b128 v[148:151], v152 offset:2048
	ds_read_b128 v[152:155], v152 offset:3072
	ds_read_b128 v[156:159], v164
	ds_read_b128 v[160:163], v164 offset:1024
	ds_read_b128 v[170:173], v164 offset:2048
	ds_read_b128 v[174:177], v164 offset:3072
	v_lshl_add_u64 v[210:211], s[18:19], 0, v[136:137]
	s_add_i32 m0, s30, 0xc000
	ds_read_b128 v[178:181], v168
	ds_read_b128 v[182:185], v168 offset:1024
	ds_read_b128 v[186:189], v168 offset:2048
	ds_read_b128 v[190:193], v168 offset:3072
	ds_read_b128 v[194:197], v168 offset:4096
	ds_read_b128 v[198:201], v168 offset:5120
	ds_read_b128 v[202:205], v168 offset:6144
	ds_read_b128 v[206:209], v168 offset:7168
	global_load_lds_dwordx4 v[210:211], off
	v_lshl_add_u64 v[210:211], s[18:19], 0, v[138:139]
	s_add_i32 m0, s30, 0xe000
	s_nop 0
	global_load_lds_dwordx4 v[210:211], off
	s_waitcnt vmcnt(8)
	s_waitcnt lgkmcnt(0)
	s_setprio 1
	s_barrier
	s_waitcnt lgkmcnt(0)
	v_mfma_f32_16x16x32_bf16 v[126:129], v[140:143], v[178:181], v[126:129]
	v_mfma_f32_16x16x32_bf16 v[118:121], v[148:151], v[178:181], v[118:121]
	v_mfma_f32_16x16x32_bf16 v[110:113], v[140:143], v[186:189], v[110:113]
	v_mfma_f32_16x16x32_bf16 v[102:105], v[148:151], v[186:189], v[102:105]
	v_mfma_f32_16x16x32_bf16 v[94:97], v[140:143], v[194:197], v[94:97]
	v_mfma_f32_16x16x32_bf16 v[86:89], v[148:151], v[194:197], v[86:89]
	v_mfma_f32_16x16x32_bf16 v[78:81], v[140:143], v[202:205], v[78:81]
	v_mfma_f32_16x16x32_bf16 v[70:73], v[148:151], v[202:205], v[70:73]
	v_mfma_f32_16x16x32_bf16 v[126:129], v[144:147], v[182:185], v[126:129]
	v_mfma_f32_16x16x32_bf16 v[118:121], v[152:155], v[182:185], v[118:121]
	v_mfma_f32_16x16x32_bf16 v[110:113], v[144:147], v[190:193], v[110:113]
	v_mfma_f32_16x16x32_bf16 v[102:105], v[152:155], v[190:193], v[102:105]
	v_mfma_f32_16x16x32_bf16 v[94:97], v[144:147], v[198:201], v[94:97]
	v_mfma_f32_16x16x32_bf16 v[86:89], v[152:155], v[198:201], v[86:89]
	v_mfma_f32_16x16x32_bf16 v[78:81], v[144:147], v[206:209], v[78:81]
	v_mfma_f32_16x16x32_bf16 v[70:73], v[152:155], v[206:209], v[70:73]
	v_mfma_f32_16x16x32_bf16 v[122:125], v[156:159], v[178:181], v[122:125]
	v_mfma_f32_16x16x32_bf16 v[114:117], v[170:173], v[178:181], v[114:117]
	v_mfma_f32_16x16x32_bf16 v[106:109], v[156:159], v[186:189], v[106:109]
	v_mfma_f32_16x16x32_bf16 v[98:101], v[170:173], v[186:189], v[98:101]
	v_mfma_f32_16x16x32_bf16 v[90:93], v[156:159], v[194:197], v[90:93]
	v_mfma_f32_16x16x32_bf16 v[82:85], v[170:173], v[194:197], v[82:85]
	v_mfma_f32_16x16x32_bf16 v[74:77], v[156:159], v[202:205], v[74:77]
	v_mfma_f32_16x16x32_bf16 v[66:69], v[170:173], v[202:205], v[66:69]
	v_mfma_f32_16x16x32_bf16 v[122:125], v[160:163], v[182:185], v[122:125]
	v_mfma_f32_16x16x32_bf16 v[114:117], v[174:177], v[182:185], v[114:117]
	v_mfma_f32_16x16x32_bf16 v[106:109], v[160:163], v[190:193], v[106:109]
	v_mfma_f32_16x16x32_bf16 v[98:101], v[174:177], v[190:193], v[98:101]
	v_mfma_f32_16x16x32_bf16 v[90:93], v[160:163], v[198:201], v[90:93]
	v_mfma_f32_16x16x32_bf16 v[82:85], v[174:177], v[198:201], v[82:85]
	v_mfma_f32_16x16x32_bf16 v[74:77], v[160:163], v[206:209], v[74:77]
	v_mfma_f32_16x16x32_bf16 v[66:69], v[174:177], v[206:209], v[66:69]
	s_barrier
	s_setprio 0
	s_add_i32 s46, s46, s29
	v_lshl_add_u64 v[210:211], s[20:21], 0, v[0:1]
	s_mov_b32 m0, s46
	ds_read_b128 v[178:181], v168 offset:16384
	ds_read_b128 v[182:185], v168 offset:17408
	ds_read_b128 v[186:189], v168 offset:18432
	ds_read_b128 v[190:193], v168 offset:19456
	ds_read_b128 v[194:197], v168 offset:20480
	ds_read_b128 v[198:201], v168 offset:21504
	ds_read_b128 v[202:205], v168 offset:22528
	ds_read_b128 v[206:209], v168 offset:23552
	global_load_lds_dwordx4 v[210:211], off
	s_add_i32 m0, s46, 0x2000
	s_add_u32 s46, s20, 0x40000
	v_lshl_add_u64 v[212:213], s[20:21], 0, v[130:131]
	s_addc_u32 s47, s21, 0
	s_add_i32 s48, s48, s29
	global_load_lds_dwordx4 v[212:213], off
	v_lshl_add_u64 v[214:215], s[46:47], 0, v[0:1]
	s_mov_b32 m0, s48
	v_lshl_add_u64 v[216:217], s[22:23], 0, v[132:133]
	global_load_lds_dwordx4 v[214:215], off
	v_lshl_add_u64 v[214:215], s[46:47], 0, v[130:131]
	s_add_i32 m0, s48, 0x2000
	s_nop 0
	global_load_lds_dwordx4 v[214:215], off
	v_lshl_add_u64 v[214:215], s[22:23], 0, v[134:135]
	s_mov_b32 m0, s30
	s_nop 0
	global_load_lds_dwordx4 v[214:215], off
	s_mov_b32 m0, s31
	s_nop 0
	global_load_lds_dwordx4 v[216:217], off
	s_waitcnt vmcnt(8)
	s_waitcnt lgkmcnt(0)
	s_setprio 1
	s_barrier
; #define PG8_STAGE(bufoff, gbase, voff) do { _Pragma("unroll") for (int _i = 0; _i < 2; ++_i) \
;         __builtin_amdgcn_global_load_lds((const unsigned*)((const char*)(gbase) + (voff)[_i]), (PG8_LAS unsigned*)(lds + (bufoff) + ldsw + _i * 8192), 16, 0, 0); } while (0)
; #define PG8_LDA(dst, b, h) do { _Pragma("unroll") for (int m = 0; m < 4; ++m) _Pragma("unroll") for (int k = 0; k < 2; ++k) dst[m][k] = *(const PG8_LAS bf16x8*)(lds + PG8_SA(b, h) + aoff + m * 2048 + k * 1024); } while (0)
; #define PG8_LDB(dst, b, h) do { _Pragma("unroll") for (int n = 0; n < 2; ++n) _Pragma("unroll") for (int k = 0; k < 2; ++k) dst[n][k] = *(const PG8_LAS bf16x8*)(lds + PG8_SB(b, h) + boff + n * 2048 + k * 1024); } while (0)
; #define PG8_MMA(ai, bj, At, Bt) do { __builtin_amdgcn_s_setprio(1); _Pragma("unroll") for (int m = 0; m < 4; ++m) _Pragma("unroll") for (int n = 0; n < 2; ++n) _Pragma("unroll") for (int k = 0; k < 2; ++k) \
;         acc[ai][bj][m][n] = __builtin_amdgcn_mfma_f32_16x16x32_bf16(Bt[n][k], At[m][k], acc[ai][bj][m][n], 0, 0, 0); __builtin_amdgcn_s_setprio(0); } while (0)
; #define PG8_WAIT_V(n) asm volatile("s_waitcnt vmcnt(" #n ")" ::: "memory")
; #define PG8_WAIT_L(n) asm volatile("s_waitcnt lgkmcnt(" #n ")" ::: "memory")
; #define PG8_BAR __builtin_amdgcn_s_barrier()
; #define PG8_SCHED __builtin_amdgcn_sched_barrier(0)
; template <class Epi, class Sched, bool ALIGN_EPI = false, bool SP2 = false>
; __device__ __forceinline__ void gemm_phase(PG8_LAS unsigned char* lds, const Gemm g, const Sched& S, const Epi& E, const int wv) {
;     ...
;             PG8_WAIT_V(8); PG8_WAIT_L(0); PG8_BAR; PG8_MMA(1, 0, At, B0); PG8_MMA(1, 1, At, B1); PG8_BAR; PG8_SCHED;
;             PG8_LDB(B0, 1, 0); PG8_LDB(B1, 1, 1); PG8_SCHED; PG8_LDA(At, 1, 0); PG8_STAGE(PG8_SA(0, 1), a2 + hstep, voffA);
;             PG8_WAIT_V(8); PG8_WAIT_L(0); PG8_BAR; PG8_MMA(0, 0, At, B0); PG8_MMA(0, 1, At, B1); PG8_BAR; PG8_SCHED;
	s_waitcnt lgkmcnt(0)
	v_mfma_f32_16x16x32_bf16 v[62:65], v[140:143], v[178:181], v[62:65]
	v_mfma_f32_16x16x32_bf16 v[54:57], v[148:151], v[178:181], v[54:57]
	v_mfma_f32_16x16x32_bf16 v[46:49], v[140:143], v[186:189], v[46:49]
	v_mfma_f32_16x16x32_bf16 v[38:41], v[148:151], v[186:189], v[38:41]
	v_mfma_f32_16x16x32_bf16 v[30:33], v[140:143], v[194:197], v[30:33]
	v_mfma_f32_16x16x32_bf16 v[22:25], v[148:151], v[194:197], v[22:25]
	v_mfma_f32_16x16x32_bf16 v[14:17], v[140:143], v[202:205], v[14:17]
	v_mfma_f32_16x16x32_bf16 v[6:9], v[148:151], v[202:205], v[6:9]
	v_mfma_f32_16x16x32_bf16 v[62:65], v[144:147], v[182:185], v[62:65]
	v_mfma_f32_16x16x32_bf16 v[54:57], v[152:155], v[182:185], v[54:57]
	v_mfma_f32_16x16x32_bf16 v[46:49], v[144:147], v[190:193], v[46:49]
	v_mfma_f32_16x16x32_bf16 v[38:41], v[152:155], v[190:193], v[38:41]
	v_mfma_f32_16x16x32_bf16 v[30:33], v[144:147], v[198:201], v[30:33]
	v_mfma_f32_16x16x32_bf16 v[22:25], v[152:155], v[198:201], v[22:25]
	v_mfma_f32_16x16x32_bf16 v[14:17], v[144:147], v[206:209], v[14:17]
	v_mfma_f32_16x16x32_bf16 v[6:9], v[152:155], v[206:209], v[6:9]
	v_mfma_f32_16x16x32_bf16 v[58:61], v[156:159], v[178:181], v[58:61]
	v_mfma_f32_16x16x32_bf16 v[50:53], v[170:173], v[178:181], v[50:53]
	v_mfma_f32_16x16x32_bf16 v[42:45], v[156:159], v[186:189], v[42:45]
	v_mfma_f32_16x16x32_bf16 v[34:37], v[170:173], v[186:189], v[34:37]
	v_mfma_f32_16x16x32_bf16 v[26:29], v[156:159], v[194:197], v[26:29]
	v_mfma_f32_16x16x32_bf16 v[18:21], v[170:173], v[194:197], v[18:21]
	v_mfma_f32_16x16x32_bf16 v[10:13], v[156:159], v[202:205], v[10:13]
	v_mfma_f32_16x16x32_bf16 v[2:5], v[170:173], v[202:205], v[2:5]
	v_mfma_f32_16x16x32_bf16 v[58:61], v[160:163], v[182:185], v[58:61]
	v_mfma_f32_16x16x32_bf16 v[50:53], v[174:177], v[182:185], v[50:53]
	v_mfma_f32_16x16x32_bf16 v[42:45], v[160:163], v[190:193], v[42:45]
	v_mfma_f32_16x16x32_bf16 v[34:37], v[174:177], v[190:193], v[34:37]
	v_mfma_f32_16x16x32_bf16 v[26:29], v[160:163], v[198:201], v[26:29]
	v_mfma_f32_16x16x32_bf16 v[18:21], v[174:177], v[198:201], v[18:21]
	v_mfma_f32_16x16x32_bf16 v[10:13], v[160:163], v[206:209], v[10:13]
	v_mfma_f32_16x16x32_bf16 v[2:5], v[174:177], v[206:209], v[2:5]
	s_barrier
	s_setprio 0
	s_add_i32 s46, 0, 0x18000
	s_add_i32 s47, 0, 0x1c000
	v_add_u32_e32 v152, s46, v166
	v_add_u32_e32 v164, s47, v166
	ds_read_b128 v[140:143], v152
	ds_read_b128 v[144:147], v152 offset:1024
	ds_read_b128 v[148:151], v152 offset:2048
	ds_read_b128 v[152:155], v152 offset:3072
	ds_read_b128 v[156:159], v164
	ds_read_b128 v[160:163], v164 offset:1024
	ds_read_b128 v[170:173], v164 offset:2048
	ds_read_b128 v[174:177], v164 offset:3072
	s_add_u32 s22, s22, 0x40000
	s_addc_u32 s23, s23, 0
	s_mov_b32 m0, s36
	v_lshl_add_u64 v[218:219], s[22:23], 0, v[134:135]
	ds_read_b128 v[178:181], v168 offset:32768
	ds_read_b128 v[182:185], v168 offset:33792
	ds_read_b128 v[186:189], v168 offset:34816
	ds_read_b128 v[190:193], v168 offset:35840
	ds_read_b128 v[194:197], v168 offset:36864
	ds_read_b128 v[198:201], v168 offset:37888
	ds_read_b128 v[202:205], v168 offset:38912
	ds_read_b128 v[206:209], v168 offset:39936
	global_load_lds_dwordx4 v[218:219], off
	v_lshl_add_u64 v[218:219], s[22:23], 0, v[132:133]
	s_mov_b32 m0, s37
	s_nop 0
	global_load_lds_dwordx4 v[218:219], off
	s_waitcnt vmcnt(8)
	s_waitcnt lgkmcnt(0)
	s_setprio 1
	s_barrier
	s_waitcnt lgkmcnt(0)
	v_mfma_f32_16x16x32_bf16 v[126:129], v[140:143], v[178:181], v[126:129]
	v_mfma_f32_16x16x32_bf16 v[118:121], v[148:151], v[178:181], v[118:121]
	v_mfma_f32_16x16x32_bf16 v[110:113], v[140:143], v[186:189], v[110:113]
	v_mfma_f32_16x16x32_bf16 v[102:105], v[148:151], v[186:189], v[102:105]
	v_mfma_f32_16x16x32_bf16 v[94:97], v[140:143], v[194:197], v[94:97]
	v_mfma_f32_16x16x32_bf16 v[86:89], v[148:151], v[194:197], v[86:89]
	v_mfma_f32_16x16x32_bf16 v[78:81], v[140:143], v[202:205], v[78:81]
	v_mfma_f32_16x16x32_bf16 v[70:73], v[148:151], v[202:205], v[70:73]
	v_mfma_f32_16x16x32_bf16 v[126:129], v[144:147], v[182:185], v[126:129]
	v_mfma_f32_16x16x32_bf16 v[118:121], v[152:155], v[182:185], v[118:121]
	v_mfma_f32_16x16x32_bf16 v[110:113], v[144:147], v[190:193], v[110:113]
	v_mfma_f32_16x16x32_bf16 v[102:105], v[152:155], v[190:193], v[102:105]
	v_mfma_f32_16x16x32_bf16 v[94:97], v[144:147], v[198:201], v[94:97]
	v_mfma_f32_16x16x32_bf16 v[86:89], v[152:155], v[198:201], v[86:89]
	v_mfma_f32_16x16x32_bf16 v[78:81], v[144:147], v[206:209], v[78:81]
	v_mfma_f32_16x16x32_bf16 v[70:73], v[152:155], v[206:209], v[70:73]
	v_mfma_f32_16x16x32_bf16 v[122:125], v[156:159], v[178:181], v[122:125]
	v_mfma_f32_16x16x32_bf16 v[114:117], v[170:173], v[178:181], v[114:117]
	v_mfma_f32_16x16x32_bf16 v[106:109], v[156:159], v[186:189], v[106:109]
	v_mfma_f32_16x16x32_bf16 v[98:101], v[170:173], v[186:189], v[98:101]
	v_mfma_f32_16x16x32_bf16 v[90:93], v[156:159], v[194:197], v[90:93]
	v_mfma_f32_16x16x32_bf16 v[82:85], v[170:173], v[194:197], v[82:85]
	v_mfma_f32_16x16x32_bf16 v[74:77], v[156:159], v[202:205], v[74:77]
	v_mfma_f32_16x16x32_bf16 v[66:69], v[170:173], v[202:205], v[66:69]
	v_mfma_f32_16x16x32_bf16 v[122:125], v[160:163], v[182:185], v[122:125]
	v_mfma_f32_16x16x32_bf16 v[114:117], v[174:177], v[182:185], v[114:117]
	v_mfma_f32_16x16x32_bf16 v[106:109], v[160:163], v[190:193], v[106:109]
	v_mfma_f32_16x16x32_bf16 v[98:101], v[174:177], v[190:193], v[98:101]
	v_mfma_f32_16x16x32_bf16 v[90:93], v[160:163], v[198:201], v[90:93]
	v_mfma_f32_16x16x32_bf16 v[82:85], v[174:177], v[198:201], v[82:85]
	v_mfma_f32_16x16x32_bf16 v[74:77], v[160:163], v[206:209], v[74:77]
	v_mfma_f32_16x16x32_bf16 v[66:69], v[174:177], v[206:209], v[66:69]
	s_barrier
; #define PG8_STAGE(bufoff, gbase, voff) do { _Pragma("unroll") for (int _i = 0; _i < 2; ++_i) \
;         __builtin_amdgcn_global_load_lds((const unsigned*)((const char*)(gbase) + (voff)[_i]), (PG8_LAS unsigned*)(lds + (bufoff) + ldsw + _i * 8192), 16, 0, 0); } while (0)
; #define PG8_LDA(dst, b, h) do { _Pragma("unroll") for (int m = 0; m < 4; ++m) _Pragma("unroll") for (int k = 0; k < 2; ++k) dst[m][k] = *(const PG8_LAS bf16x8*)(lds + PG8_SA(b, h) + aoff + m * 2048 + k * 1024); } while (0)
; #define PG8_MMA(ai, bj, At, Bt) do { __builtin_amdgcn_s_setprio(1); _Pragma("unroll") for (int m = 0; m < 4; ++m) _Pragma("unroll") for (int n = 0; n < 2; ++n) _Pragma("unroll") for (int k = 0; k < 2; ++k) \
;         acc[ai][bj][m][n] = __builtin_amdgcn_mfma_f32_16x16x32_bf16(Bt[n][k], At[m][k], acc[ai][bj][m][n], 0, 0, 0); __builtin_amdgcn_s_setprio(0); } while (0)
; #define PG8_WAIT_V(n) asm volatile("s_waitcnt vmcnt(" #n ")" ::: "memory")
; #define PG8_WAIT_L(n) asm volatile("s_waitcnt lgkmcnt(" #n ")" ::: "memory")
; #define PG8_BAR __builtin_amdgcn_s_barrier()
; #define PG8_SCHED __builtin_amdgcn_sched_barrier(0)
; template <class Epi, class Sched, bool ALIGN_EPI = false, bool SP2 = false>
; __device__ __forceinline__ void gemm_phase(PG8_LAS unsigned char* lds, const Gemm g, const Sched& S, const Epi& E, const int wv) {
;     ...
;             PG8_LDA(At, 1, 1); PG8_STAGE(PG8_SB(1, 0), b3, voffB); PG8_STAGE(PG8_SB(1, 1), b3 + hstep, voffB); PG8_STAGE(PG8_SA(1, 0), a3, voffA);
;             PG8_WAIT_V(8); PG8_WAIT_L(0); PG8_BAR; PG8_MMA(1, 0, At, B0); PG8_MMA(1, 1, At, B1); PG8_BAR; PG8_SCHED;
	s_setprio 0
	s_add_i32 s22, s46, s29
	v_lshl_add_u64 v[210:211], v[210:211], 0, s[2:3]
	s_mov_b32 m0, s22
	ds_read_b128 v[178:181], v168 offset:49152
	ds_read_b128 v[182:185], v168 offset:50176
	ds_read_b128 v[186:189], v168 offset:51200
	ds_read_b128 v[190:193], v168 offset:52224
	ds_read_b128 v[194:197], v168 offset:53248
	ds_read_b128 v[198:201], v168 offset:54272
	ds_read_b128 v[202:205], v168 offset:55296
	ds_read_b128 v[206:209], v168 offset:56320
	global_load_lds_dwordx4 v[210:211], off
	s_add_i32 m0, s22, 0x2000
	s_add_u32 s20, s20, 0x40080
	v_lshl_add_u64 v[210:211], v[212:213], 0, s[2:3]
	s_addc_u32 s21, s21, 0
	s_add_i32 s22, s47, s29
	global_load_lds_dwordx4 v[210:211], off
	v_lshl_add_u64 v[210:211], s[20:21], 0, v[0:1]
	s_mov_b32 m0, s22
	s_nop 0
	global_load_lds_dwordx4 v[210:211], off
	v_lshl_add_u64 v[210:211], s[20:21], 0, v[130:131]
	s_add_i32 m0, s22, 0x2000
	s_nop 0
	global_load_lds_dwordx4 v[210:211], off
	v_lshl_add_u64 v[210:211], v[214:215], 0, s[2:3]
	s_mov_b32 m0, s39
	s_nop 0
	global_load_lds_dwordx4 v[210:211], off
	v_lshl_add_u64 v[210:211], v[216:217], 0, s[2:3]
	s_mov_b32 m0, s40
	s_nop 0
	global_load_lds_dwordx4 v[210:211], off
	s_waitcnt vmcnt(8)
	s_waitcnt lgkmcnt(0)
	s_setprio 1
	s_barrier
	s_waitcnt lgkmcnt(0)
	v_mfma_f32_16x16x32_bf16 v[62:65], v[140:143], v[178:181], v[62:65]
	v_mfma_f32_16x16x32_bf16 v[54:57], v[148:151], v[178:181], v[54:57]
	v_mfma_f32_16x16x32_bf16 v[46:49], v[140:143], v[186:189], v[46:49]
	v_mfma_f32_16x16x32_bf16 v[38:41], v[148:151], v[186:189], v[38:41]
	v_mfma_f32_16x16x32_bf16 v[30:33], v[140:143], v[194:197], v[30:33]
	v_mfma_f32_16x16x32_bf16 v[22:25], v[148:151], v[194:197], v[22:25]
	v_mfma_f32_16x16x32_bf16 v[14:17], v[140:143], v[202:205], v[14:17]
	v_mfma_f32_16x16x32_bf16 v[6:9], v[148:151], v[202:205], v[6:9]
	v_mfma_f32_16x16x32_bf16 v[62:65], v[144:147], v[182:185], v[62:65]
	v_mfma_f32_16x16x32_bf16 v[54:57], v[152:155], v[182:185], v[54:57]
	v_mfma_f32_16x16x32_bf16 v[46:49], v[144:147], v[190:193], v[46:49]
	v_mfma_f32_16x16x32_bf16 v[38:41], v[152:155], v[190:193], v[38:41]
	v_mfma_f32_16x16x32_bf16 v[30:33], v[144:147], v[198:201], v[30:33]
	v_mfma_f32_16x16x32_bf16 v[22:25], v[152:155], v[198:201], v[22:25]
	v_mfma_f32_16x16x32_bf16 v[14:17], v[144:147], v[206:209], v[14:17]
	v_mfma_f32_16x16x32_bf16 v[6:9], v[152:155], v[206:209], v[6:9]
	v_mfma_f32_16x16x32_bf16 v[58:61], v[156:159], v[178:181], v[58:61]
	v_mfma_f32_16x16x32_bf16 v[50:53], v[170:173], v[178:181], v[50:53]
	v_mfma_f32_16x16x32_bf16 v[42:45], v[156:159], v[186:189], v[42:45]
	v_mfma_f32_16x16x32_bf16 v[34:37], v[170:173], v[186:189], v[34:37]
	v_mfma_f32_16x16x32_bf16 v[26:29], v[156:159], v[194:197], v[26:29]
	v_mfma_f32_16x16x32_bf16 v[18:21], v[170:173], v[194:197], v[18:21]
	v_mfma_f32_16x16x32_bf16 v[10:13], v[156:159], v[202:205], v[10:13]
	v_mfma_f32_16x16x32_bf16 v[2:5], v[170:173], v[202:205], v[2:5]
	v_mfma_f32_16x16x32_bf16 v[58:61], v[160:163], v[182:185], v[58:61]
	v_mfma_f32_16x16x32_bf16 v[50:53], v[174:177], v[182:185], v[50:53]
	v_mfma_f32_16x16x32_bf16 v[42:45], v[160:163], v[190:193], v[42:45]
	v_mfma_f32_16x16x32_bf16 v[34:37], v[174:177], v[190:193], v[34:37]
	v_mfma_f32_16x16x32_bf16 v[26:29], v[160:163], v[198:201], v[26:29]
	v_mfma_f32_16x16x32_bf16 v[18:21], v[174:177], v[198:201], v[18:21]
	v_mfma_f32_16x16x32_bf16 v[10:13], v[160:163], v[206:209], v[10:13]
	v_mfma_f32_16x16x32_bf16 v[2:5], v[174:177], v[206:209], v[2:5]
	s_barrier
	s_setprio 0
	s_add_i32 s45, s45, 2
	s_add_u32 s18, s18, 0x100
	s_addc_u32 s19, s19, 0
	s_add_u32 s43, s43, 0x100
	s_addc_u32 s44, s44, 0
	s_cmp_gt_u32 s45, 13
	s_cbranch_scc0 .LBB0_428
	s_and_b64 vcc, exec, s[6:7]
	s_cbranch_vccz .LBB0_431
	s_barrier

; #define PG8_STAGE(bufoff, gbase, voff) do { _Pragma("unroll") for (int _i = 0; _i < 2; ++_i) \
;         __builtin_amdgcn_global_load_lds((const unsigned*)((const char*)(gbase) + (voff)[_i]), (PG8_LAS unsigned*)(lds + (bufoff) + ldsw + _i * 8192), 16, 0, 0); } while (0)
; #define PG8_LDA(dst, b, h) do { _Pragma("unroll") for (int m = 0; m < 4; ++m) _Pragma("unroll") for (int k = 0; k < 2; ++k) dst[m][k] = *(const PG8_LAS bf16x8*)(lds + PG8_SA(b, h) + aoff + m * 2048 + k * 1024); } while (0)
; #define PG8_LDB(dst, b, h) do { _Pragma("unroll") for (int n = 0; n < 2; ++n) _Pragma("unroll") for (int k = 0; k < 2; ++k) dst[n][k] = *(const PG8_LAS bf16x8*)(lds + PG8_SB(b, h) + boff + n * 2048 + k * 1024); } while (0)
; #define PG8_MMA(ai, bj, At, Bt) do { __builtin_amdgcn_s_setprio(1); _Pragma("unroll") for (int m = 0; m < 4; ++m) _Pragma("unroll") for (int n = 0; n < 2; ++n) _Pragma("unroll") for (int k = 0; k < 2; ++k) \
;         acc[ai][bj][m][n] = __builtin_amdgcn_mfma_f32_16x16x32_bf16(Bt[n][k], At[m][k], acc[ai][bj][m][n], 0, 0, 0); __builtin_amdgcn_s_setprio(0); } while (0)
; #define PG8_WAIT_V(n) asm volatile("s_waitcnt vmcnt(" #n ")" ::: "memory")
; #define PG8_WAIT_L(n) asm volatile("s_waitcnt lgkmcnt(" #n ")" ::: "memory")
; #define PG8_BAR __builtin_amdgcn_s_barrier()
; #define PG8_SCHED __builtin_amdgcn_sched_barrier(0)
; template <class Epi, class Sched, bool ALIGN_EPI = false, bool SP2 = false>
; __device__ __forceinline__ void gemm_phase(PG8_LAS unsigned char* lds, const Gemm g, const Sched& S, const Epi& E, const int wv) {
;     ...
;             const bool last = (t == nt - 2);
;             const char* a1 = cA + (size_t)(t + 1) * kstep;
;             const char* a2 = last ? nA : cA + (size_t)(t + 2) * kstep; const char* b2 = last ? nB : cB + (size_t)(t + 2) * kstep;
;             const char* a3 = a2 + kstep; const char* b3 = b2 + kstep;
;             if (last && has_next) S.a_ready(nxt);
;             if constexpr (SP2) {
;             PG8_LDB(B0, 0, 0); PG8_LDB(B1, 0, 1); PG8_SCHED; PG8_LDA(At, 0, 0); PG8_STAGE(PG8_SA(1, 1), a1 + hstep, voffA);
;             PG8_WAIT_V(8); PG8_WAIT_L(0); PG8_BAR; PG8_MMA(0, 0, At, B0); PG8_MMA(0, 1, At, B1); PG8_BAR; PG8_SCHED;
;             PG8_LDA(At, 0, 1); PG8_STAGE(PG8_SB(0, 0), b2, voffB); PG8_STAGE(PG8_SB(0, 1), b2 + hstep, voffB); PG8_STAGE(PG8_SA(0, 0), a2, voffA);
.LBB0_504:
	s_add_u32 s10, s8, 0x100
	s_addc_u32 s11, s9, 0
	s_add_i32 s52, 0, 0x10000
	s_cmp_eq_u32 s51, 40
	s_cselect_b32 s29, s1, s11
	s_cselect_b32 s28, s0, s10
	s_cselect_b32 s27, s25, s50
	s_cselect_b32 s26, s24, s49
	s_add_i32 s53, 0, 0x14000
	v_add_u32_e32 v142, s52, v187
	v_add_u32_e32 v168, s53, v187
	ds_read_b128 v[122:125], v142
	ds_read_b128 v[130:133], v142 offset:1024
	ds_read_b128 v[138:141], v142 offset:2048
	ds_read_b128 v[142:145], v142 offset:3072
	ds_read_b128 v[146:149], v168
	ds_read_b128 v[150:153], v168 offset:1024
	ds_read_b128 v[154:157], v168 offset:2048
	ds_read_b128 v[168:171], v168 offset:3072
	v_lshl_add_u64 v[184:185], s[8:9], 0, v[164:165]
	s_add_i32 m0, s37, 0xc000
	ds_read_b128 v[172:175], v189
	ds_read_b128 v[176:179], v189 offset:1024
	ds_read_b128 v[180:183], v189 offset:2048
	ds_read_b128 v[190:193], v189 offset:3072
	ds_read_b128 v[194:197], v189 offset:4096
	ds_read_b128 v[198:201], v189 offset:5120
	ds_read_b128 v[202:205], v189 offset:6144
	ds_read_b128 v[206:209], v189 offset:7168
	global_load_lds_dwordx4 v[184:185], off
	v_lshl_add_u64 v[184:185], s[8:9], 0, v[166:167]
	s_add_i32 m0, s37, 0xe000
	s_nop 0
	global_load_lds_dwordx4 v[184:185], off
	s_waitcnt vmcnt(8)
	s_waitcnt lgkmcnt(0)
	s_setprio 1
	s_barrier
	s_waitcnt lgkmcnt(0)
	v_mfma_f32_16x16x32_bf16 v[134:137], v[122:125], v[172:175], v[134:137]
	v_mfma_f32_16x16x32_bf16 v[126:129], v[138:141], v[172:175], v[126:129]
	v_mfma_f32_16x16x32_bf16 v[110:113], v[122:125], v[180:183], v[110:113]
	v_mfma_f32_16x16x32_bf16 v[106:109], v[138:141], v[180:183], v[106:109]
	v_mfma_f32_16x16x32_bf16 v[94:97], v[122:125], v[194:197], v[94:97]
	v_mfma_f32_16x16x32_bf16 v[90:93], v[138:141], v[194:197], v[90:93]
	v_mfma_f32_16x16x32_bf16 v[78:81], v[122:125], v[202:205], v[78:81]
	v_mfma_f32_16x16x32_bf16 v[74:77], v[138:141], v[202:205], v[74:77]
	v_mfma_f32_16x16x32_bf16 v[134:137], v[130:133], v[176:179], v[134:137]
	v_mfma_f32_16x16x32_bf16 v[126:129], v[142:145], v[176:179], v[126:129]
	v_mfma_f32_16x16x32_bf16 v[110:113], v[130:133], v[190:193], v[110:113]
	v_mfma_f32_16x16x32_bf16 v[106:109], v[142:145], v[190:193], v[106:109]
	v_mfma_f32_16x16x32_bf16 v[94:97], v[130:133], v[198:201], v[94:97]
	v_mfma_f32_16x16x32_bf16 v[90:93], v[142:145], v[198:201], v[90:93]
	v_mfma_f32_16x16x32_bf16 v[78:81], v[130:133], v[206:209], v[78:81]
	v_mfma_f32_16x16x32_bf16 v[74:77], v[142:145], v[206:209], v[74:77]
	v_mfma_f32_16x16x32_bf16 v[118:121], v[146:149], v[172:175], v[118:121]
	v_mfma_f32_16x16x32_bf16 v[114:117], v[154:157], v[172:175], v[114:117]
	v_mfma_f32_16x16x32_bf16 v[102:105], v[146:149], v[180:183], v[102:105]
	v_mfma_f32_16x16x32_bf16 v[98:101], v[154:157], v[180:183], v[98:101]
	v_mfma_f32_16x16x32_bf16 v[86:89], v[146:149], v[194:197], v[86:89]
	v_mfma_f32_16x16x32_bf16 v[82:85], v[154:157], v[194:197], v[82:85]
	v_mfma_f32_16x16x32_bf16 v[70:73], v[146:149], v[202:205], v[70:73]
	v_mfma_f32_16x16x32_bf16 v[66:69], v[154:157], v[202:205], v[66:69]
	v_mfma_f32_16x16x32_bf16 v[118:121], v[150:153], v[176:179], v[118:121]
	v_mfma_f32_16x16x32_bf16 v[114:117], v[168:171], v[176:179], v[114:117]
	v_mfma_f32_16x16x32_bf16 v[102:105], v[150:153], v[190:193], v[102:105]
	v_mfma_f32_16x16x32_bf16 v[98:101], v[168:171], v[190:193], v[98:101]
	v_mfma_f32_16x16x32_bf16 v[86:89], v[150:153], v[198:201], v[86:89]
	v_mfma_f32_16x16x32_bf16 v[82:85], v[168:171], v[198:201], v[82:85]
	v_mfma_f32_16x16x32_bf16 v[70:73], v[150:153], v[206:209], v[70:73]
	v_mfma_f32_16x16x32_bf16 v[66:69], v[168:171], v[206:209], v[66:69]
	s_barrier
	s_setprio 0
	s_add_i32 s8, s52, s36
	v_lshl_add_u64 v[184:185], s[26:27], 0, v[0:1]
	s_mov_b32 m0, s8
	ds_read_b128 v[172:175], v189 offset:16384
	ds_read_b128 v[176:179], v189 offset:17408
	ds_read_b128 v[180:183], v189 offset:18432
	ds_read_b128 v[190:193], v189 offset:19456
	ds_read_b128 v[194:197], v189 offset:20480
	ds_read_b128 v[198:201], v189 offset:21504
	ds_read_b128 v[202:205], v189 offset:22528
	ds_read_b128 v[206:209], v189 offset:23552
	global_load_lds_dwordx4 v[184:185], off
	s_add_i32 m0, s8, 0x2000
	s_add_u32 s8, s26, 0xb0000
	v_lshl_add_u64 v[210:211], s[26:27], 0, v[162:163]
	s_addc_u32 s9, s27, 0
	s_add_i32 s52, s53, s36
	global_load_lds_dwordx4 v[210:211], off
	v_lshl_add_u64 v[212:213], s[8:9], 0, v[0:1]
	s_mov_b32 m0, s52
	v_lshl_add_u64 v[214:215], s[28:29], 0, v[160:161]
	global_load_lds_dwordx4 v[212:213], off
	v_lshl_add_u64 v[212:213], s[8:9], 0, v[162:163]
	s_add_i32 m0, s52, 0x2000
	s_nop 0
	global_load_lds_dwordx4 v[212:213], off
	v_lshl_add_u64 v[212:213], s[28:29], 0, v[158:159]
	s_mov_b32 m0, s37
	s_nop 0
	global_load_lds_dwordx4 v[212:213], off
	s_mov_b32 m0, s38
	s_nop 0
	global_load_lds_dwordx4 v[214:215], off
	s_waitcnt vmcnt(8)
	s_waitcnt lgkmcnt(0)
	s_setprio 1
	s_barrier
; #define PG8_STAGE(bufoff, gbase, voff) do { _Pragma("unroll") for (int _i = 0; _i < 2; ++_i) \
;         __builtin_amdgcn_global_load_lds((const unsigned*)((const char*)(gbase) + (voff)[_i]), (PG8_LAS unsigned*)(lds + (bufoff) + ldsw + _i * 8192), 16, 0, 0); } while (0)
; #define PG8_LDA(dst, b, h) do { _Pragma("unroll") for (int m = 0; m < 4; ++m) _Pragma("unroll") for (int k = 0; k < 2; ++k) dst[m][k] = *(const PG8_LAS bf16x8*)(lds + PG8_SA(b, h) + aoff + m * 2048 + k * 1024); } while (0)
; #define PG8_LDB(dst, b, h) do { _Pragma("unroll") for (int n = 0; n < 2; ++n) _Pragma("unroll") for (int k = 0; k < 2; ++k) dst[n][k] = *(const PG8_LAS bf16x8*)(lds + PG8_SB(b, h) + boff + n * 2048 + k * 1024); } while (0)
; #define PG8_MMA(ai, bj, At, Bt) do { __builtin_amdgcn_s_setprio(1); _Pragma("unroll") for (int m = 0; m < 4; ++m) _Pragma("unroll") for (int n = 0; n < 2; ++n) _Pragma("unroll") for (int k = 0; k < 2; ++k) \
;         acc[ai][bj][m][n] = __builtin_amdgcn_mfma_f32_16x16x32_bf16(Bt[n][k], At[m][k], acc[ai][bj][m][n], 0, 0, 0); __builtin_amdgcn_s_setprio(0); } while (0)
; #define PG8_WAIT_V(n) asm volatile("s_waitcnt vmcnt(" #n ")" ::: "memory")
; #define PG8_WAIT_L(n) asm volatile("s_waitcnt lgkmcnt(" #n ")" ::: "memory")
; #define PG8_BAR __builtin_amdgcn_s_barrier()
; #define PG8_SCHED __builtin_amdgcn_sched_barrier(0)
; template <class Epi, class Sched, bool ALIGN_EPI = false, bool SP2 = false>
; __device__ __forceinline__ void gemm_phase(PG8_LAS unsigned char* lds, const Gemm g, const Sched& S, const Epi& E, const int wv) {
;     ...
;             PG8_WAIT_V(8); PG8_WAIT_L(0); PG8_BAR; PG8_MMA(1, 0, At, B0); PG8_MMA(1, 1, At, B1); PG8_BAR; PG8_SCHED;
;             PG8_LDB(B0, 1, 0); PG8_LDB(B1, 1, 1); PG8_SCHED; PG8_LDA(At, 1, 0); PG8_STAGE(PG8_SA(0, 1), a2 + hstep, voffA);
;             PG8_WAIT_V(8); PG8_WAIT_L(0); PG8_BAR; PG8_MMA(0, 0, At, B0); PG8_MMA(0, 1, At, B1); PG8_BAR; PG8_SCHED;
	s_waitcnt lgkmcnt(0)
	v_mfma_f32_16x16x32_bf16 v[62:65], v[122:125], v[172:175], v[62:65]
	v_mfma_f32_16x16x32_bf16 v[58:61], v[138:141], v[172:175], v[58:61]
	v_mfma_f32_16x16x32_bf16 v[46:49], v[122:125], v[180:183], v[46:49]
	v_mfma_f32_16x16x32_bf16 v[42:45], v[138:141], v[180:183], v[42:45]
	v_mfma_f32_16x16x32_bf16 v[30:33], v[122:125], v[194:197], v[30:33]
	v_mfma_f32_16x16x32_bf16 v[26:29], v[138:141], v[194:197], v[26:29]
	v_mfma_f32_16x16x32_bf16 v[14:17], v[122:125], v[202:205], v[14:17]
	v_mfma_f32_16x16x32_bf16 v[10:13], v[138:141], v[202:205], v[10:13]
	v_mfma_f32_16x16x32_bf16 v[62:65], v[130:133], v[176:179], v[62:65]
	v_mfma_f32_16x16x32_bf16 v[58:61], v[142:145], v[176:179], v[58:61]
	v_mfma_f32_16x16x32_bf16 v[46:49], v[130:133], v[190:193], v[46:49]
	v_mfma_f32_16x16x32_bf16 v[42:45], v[142:145], v[190:193], v[42:45]
	v_mfma_f32_16x16x32_bf16 v[30:33], v[130:133], v[198:201], v[30:33]
	v_mfma_f32_16x16x32_bf16 v[26:29], v[142:145], v[198:201], v[26:29]
	v_mfma_f32_16x16x32_bf16 v[14:17], v[130:133], v[206:209], v[14:17]
	v_mfma_f32_16x16x32_bf16 v[10:13], v[142:145], v[206:209], v[10:13]
	v_mfma_f32_16x16x32_bf16 v[54:57], v[146:149], v[172:175], v[54:57]
	v_mfma_f32_16x16x32_bf16 v[50:53], v[154:157], v[172:175], v[50:53]
	v_mfma_f32_16x16x32_bf16 v[38:41], v[146:149], v[180:183], v[38:41]
	v_mfma_f32_16x16x32_bf16 v[34:37], v[154:157], v[180:183], v[34:37]
	v_mfma_f32_16x16x32_bf16 v[22:25], v[146:149], v[194:197], v[22:25]
	v_mfma_f32_16x16x32_bf16 v[18:21], v[154:157], v[194:197], v[18:21]
	v_mfma_f32_16x16x32_bf16 v[6:9], v[146:149], v[202:205], v[6:9]
	v_mfma_f32_16x16x32_bf16 v[2:5], v[154:157], v[202:205], v[2:5]
	v_mfma_f32_16x16x32_bf16 v[54:57], v[150:153], v[176:179], v[54:57]
	v_mfma_f32_16x16x32_bf16 v[50:53], v[168:171], v[176:179], v[50:53]
	v_mfma_f32_16x16x32_bf16 v[38:41], v[150:153], v[190:193], v[38:41]
	v_mfma_f32_16x16x32_bf16 v[34:37], v[168:171], v[190:193], v[34:37]
	v_mfma_f32_16x16x32_bf16 v[22:25], v[150:153], v[198:201], v[22:25]
	v_mfma_f32_16x16x32_bf16 v[18:21], v[168:171], v[198:201], v[18:21]
	v_mfma_f32_16x16x32_bf16 v[6:9], v[150:153], v[206:209], v[6:9]
	v_mfma_f32_16x16x32_bf16 v[2:5], v[168:171], v[206:209], v[2:5]
	s_barrier
	s_setprio 0
	s_add_i32 s52, 0, 0x18000
	s_add_i32 s53, 0, 0x1c000
	v_add_u32_e32 v142, s52, v187
	v_add_u32_e32 v168, s53, v187
	ds_read_b128 v[122:125], v142
	ds_read_b128 v[130:133], v142 offset:1024
	ds_read_b128 v[138:141], v142 offset:2048
	ds_read_b128 v[142:145], v142 offset:3072
	ds_read_b128 v[146:149], v168
	ds_read_b128 v[150:153], v168 offset:1024
	ds_read_b128 v[154:157], v168 offset:2048
	ds_read_b128 v[168:171], v168 offset:3072
	s_add_u32 s8, s28, 0xb0000
	s_addc_u32 s9, s29, 0
	s_mov_b32 m0, s39
	v_lshl_add_u64 v[216:217], s[8:9], 0, v[158:159]
	ds_read_b128 v[172:175], v189 offset:32768
	ds_read_b128 v[176:179], v189 offset:33792
	ds_read_b128 v[180:183], v189 offset:34816
	ds_read_b128 v[190:193], v189 offset:35840
	ds_read_b128 v[194:197], v189 offset:36864
	ds_read_b128 v[198:201], v189 offset:37888
	ds_read_b128 v[202:205], v189 offset:38912
	ds_read_b128 v[206:209], v189 offset:39936
	global_load_lds_dwordx4 v[216:217], off
	v_lshl_add_u64 v[216:217], s[8:9], 0, v[160:161]
	s_mov_b32 m0, s40
	s_nop 0
	global_load_lds_dwordx4 v[216:217], off
	s_waitcnt vmcnt(8)
	s_waitcnt lgkmcnt(0)
	s_setprio 1
	s_barrier
	s_waitcnt lgkmcnt(0)
	v_mfma_f32_16x16x32_bf16 v[134:137], v[122:125], v[172:175], v[134:137]
	v_mfma_f32_16x16x32_bf16 v[126:129], v[138:141], v[172:175], v[126:129]
	v_mfma_f32_16x16x32_bf16 v[110:113], v[122:125], v[180:183], v[110:113]
	v_mfma_f32_16x16x32_bf16 v[106:109], v[138:141], v[180:183], v[106:109]
	v_mfma_f32_16x16x32_bf16 v[94:97], v[122:125], v[194:197], v[94:97]
	v_mfma_f32_16x16x32_bf16 v[90:93], v[138:141], v[194:197], v[90:93]
	v_mfma_f32_16x16x32_bf16 v[78:81], v[122:125], v[202:205], v[78:81]
	v_mfma_f32_16x16x32_bf16 v[74:77], v[138:141], v[202:205], v[74:77]
	v_mfma_f32_16x16x32_bf16 v[134:137], v[130:133], v[176:179], v[134:137]
	v_mfma_f32_16x16x32_bf16 v[126:129], v[142:145], v[176:179], v[126:129]
	v_mfma_f32_16x16x32_bf16 v[110:113], v[130:133], v[190:193], v[110:113]
	v_mfma_f32_16x16x32_bf16 v[106:109], v[142:145], v[190:193], v[106:109]
	v_mfma_f32_16x16x32_bf16 v[94:97], v[130:133], v[198:201], v[94:97]
	v_mfma_f32_16x16x32_bf16 v[90:93], v[142:145], v[198:201], v[90:93]
	v_mfma_f32_16x16x32_bf16 v[78:81], v[130:133], v[206:209], v[78:81]
	v_mfma_f32_16x16x32_bf16 v[74:77], v[142:145], v[206:209], v[74:77]
	v_mfma_f32_16x16x32_bf16 v[118:121], v[146:149], v[172:175], v[118:121]
	v_mfma_f32_16x16x32_bf16 v[114:117], v[154:157], v[172:175], v[114:117]
	v_mfma_f32_16x16x32_bf16 v[102:105], v[146:149], v[180:183], v[102:105]
	v_mfma_f32_16x16x32_bf16 v[98:101], v[154:157], v[180:183], v[98:101]
	v_mfma_f32_16x16x32_bf16 v[86:89], v[146:149], v[194:197], v[86:89]
	v_mfma_f32_16x16x32_bf16 v[82:85], v[154:157], v[194:197], v[82:85]
	v_mfma_f32_16x16x32_bf16 v[70:73], v[146:149], v[202:205], v[70:73]
	v_mfma_f32_16x16x32_bf16 v[66:69], v[154:157], v[202:205], v[66:69]
	v_mfma_f32_16x16x32_bf16 v[118:121], v[150:153], v[176:179], v[118:121]
	v_mfma_f32_16x16x32_bf16 v[114:117], v[168:171], v[176:179], v[114:117]
	v_mfma_f32_16x16x32_bf16 v[102:105], v[150:153], v[190:193], v[102:105]
	v_mfma_f32_16x16x32_bf16 v[98:101], v[168:171], v[190:193], v[98:101]
	v_mfma_f32_16x16x32_bf16 v[86:89], v[150:153], v[198:201], v[86:89]
	v_mfma_f32_16x16x32_bf16 v[82:85], v[168:171], v[198:201], v[82:85]
	v_mfma_f32_16x16x32_bf16 v[70:73], v[150:153], v[206:209], v[70:73]
	v_mfma_f32_16x16x32_bf16 v[66:69], v[168:171], v[206:209], v[66:69]
	s_barrier
; #define PG8_STAGE(bufoff, gbase, voff) do { _Pragma("unroll") for (int _i = 0; _i < 2; ++_i) \
;         __builtin_amdgcn_global_load_lds((const unsigned*)((const char*)(gbase) + (voff)[_i]), (PG8_LAS unsigned*)(lds + (bufoff) + ldsw + _i * 8192), 16, 0, 0); } while (0)
; #define PG8_LDA(dst, b, h) do { _Pragma("unroll") for (int m = 0; m < 4; ++m) _Pragma("unroll") for (int k = 0; k < 2; ++k) dst[m][k] = *(const PG8_LAS bf16x8*)(lds + PG8_SA(b, h) + aoff + m * 2048 + k * 1024); } while (0)
; #define PG8_MMA(ai, bj, At, Bt) do { __builtin_amdgcn_s_setprio(1); _Pragma("unroll") for (int m = 0; m < 4; ++m) _Pragma("unroll") for (int n = 0; n < 2; ++n) _Pragma("unroll") for (int k = 0; k < 2; ++k) \
;         acc[ai][bj][m][n] = __builtin_amdgcn_mfma_f32_16x16x32_bf16(Bt[n][k], At[m][k], acc[ai][bj][m][n], 0, 0, 0); __builtin_amdgcn_s_setprio(0); } while (0)
; #define PG8_WAIT_V(n) asm volatile("s_waitcnt vmcnt(" #n ")" ::: "memory")
; #define PG8_WAIT_L(n) asm volatile("s_waitcnt lgkmcnt(" #n ")" ::: "memory")
; #define PG8_BAR __builtin_amdgcn_s_barrier()
; #define PG8_SCHED __builtin_amdgcn_sched_barrier(0)
; template <class Epi, class Sched, bool ALIGN_EPI = false, bool SP2 = false>
; __device__ __forceinline__ void gemm_phase(PG8_LAS unsigned char* lds, const Gemm g, const Sched& S, const Epi& E, const int wv) {
;     ...
;             PG8_LDA(At, 1, 1); PG8_STAGE(PG8_SB(1, 0), b3, voffB); PG8_STAGE(PG8_SB(1, 1), b3 + hstep, voffB); PG8_STAGE(PG8_SA(1, 0), a3, voffA);
;             PG8_WAIT_V(8); PG8_WAIT_L(0); PG8_BAR; PG8_MMA(1, 0, At, B0); PG8_MMA(1, 1, At, B1); PG8_BAR; PG8_SCHED;
	s_setprio 0
	s_add_i32 s8, s52, s36
	v_lshl_add_u64 v[184:185], v[184:185], 0, s[2:3]
	s_mov_b32 m0, s8
	ds_read_b128 v[172:175], v189 offset:49152
	ds_read_b128 v[176:179], v189 offset:50176
	ds_read_b128 v[180:183], v189 offset:51200
	ds_read_b128 v[190:193], v189 offset:52224
	ds_read_b128 v[194:197], v189 offset:53248
	ds_read_b128 v[198:201], v189 offset:54272
	ds_read_b128 v[202:205], v189 offset:55296
	ds_read_b128 v[206:209], v189 offset:56320
	global_load_lds_dwordx4 v[184:185], off
	s_add_i32 m0, s8, 0x2000
	s_add_u32 s8, s26, 0xb0080
	v_lshl_add_u64 v[184:185], v[210:211], 0, s[2:3]
	s_addc_u32 s9, s27, 0
	s_add_i32 s26, s53, s36
	global_load_lds_dwordx4 v[184:185], off
	v_lshl_add_u64 v[184:185], s[8:9], 0, v[0:1]
	s_mov_b32 m0, s26
	s_nop 0
	global_load_lds_dwordx4 v[184:185], off
	v_lshl_add_u64 v[184:185], s[8:9], 0, v[162:163]
	s_add_i32 m0, s26, 0x2000
	s_nop 0
	global_load_lds_dwordx4 v[184:185], off
	v_lshl_add_u64 v[184:185], v[212:213], 0, s[2:3]
	s_mov_b32 m0, s42
	s_nop 0
	global_load_lds_dwordx4 v[184:185], off
	v_lshl_add_u64 v[184:185], v[214:215], 0, s[2:3]
	s_mov_b32 m0, s43
	s_nop 0
	global_load_lds_dwordx4 v[184:185], off
	s_waitcnt vmcnt(8)
	s_waitcnt lgkmcnt(0)
	s_setprio 1
	s_barrier
	s_waitcnt lgkmcnt(0)
	v_mfma_f32_16x16x32_bf16 v[62:65], v[122:125], v[172:175], v[62:65]
	v_mfma_f32_16x16x32_bf16 v[58:61], v[138:141], v[172:175], v[58:61]
	v_mfma_f32_16x16x32_bf16 v[46:49], v[122:125], v[180:183], v[46:49]
	v_mfma_f32_16x16x32_bf16 v[42:45], v[138:141], v[180:183], v[42:45]
	v_mfma_f32_16x16x32_bf16 v[30:33], v[122:125], v[194:197], v[30:33]
	v_mfma_f32_16x16x32_bf16 v[26:29], v[138:141], v[194:197], v[26:29]
	v_mfma_f32_16x16x32_bf16 v[14:17], v[122:125], v[202:205], v[14:17]
	v_mfma_f32_16x16x32_bf16 v[10:13], v[138:141], v[202:205], v[10:13]
	v_mfma_f32_16x16x32_bf16 v[62:65], v[130:133], v[176:179], v[62:65]
	v_mfma_f32_16x16x32_bf16 v[58:61], v[142:145], v[176:179], v[58:61]
	v_mfma_f32_16x16x32_bf16 v[46:49], v[130:133], v[190:193], v[46:49]
	v_mfma_f32_16x16x32_bf16 v[42:45], v[142:145], v[190:193], v[42:45]
	v_mfma_f32_16x16x32_bf16 v[30:33], v[130:133], v[198:201], v[30:33]
	v_mfma_f32_16x16x32_bf16 v[26:29], v[142:145], v[198:201], v[26:29]
	v_mfma_f32_16x16x32_bf16 v[14:17], v[130:133], v[206:209], v[14:17]
	v_mfma_f32_16x16x32_bf16 v[10:13], v[142:145], v[206:209], v[10:13]
	v_mfma_f32_16x16x32_bf16 v[54:57], v[146:149], v[172:175], v[54:57]
	v_mfma_f32_16x16x32_bf16 v[50:53], v[154:157], v[172:175], v[50:53]
	v_mfma_f32_16x16x32_bf16 v[38:41], v[146:149], v[180:183], v[38:41]
	v_mfma_f32_16x16x32_bf16 v[34:37], v[154:157], v[180:183], v[34:37]
	v_mfma_f32_16x16x32_bf16 v[22:25], v[146:149], v[194:197], v[22:25]
	v_mfma_f32_16x16x32_bf16 v[18:21], v[154:157], v[194:197], v[18:21]
	v_mfma_f32_16x16x32_bf16 v[6:9], v[146:149], v[202:205], v[6:9]
	v_mfma_f32_16x16x32_bf16 v[2:5], v[154:157], v[202:205], v[2:5]
	v_mfma_f32_16x16x32_bf16 v[54:57], v[150:153], v[176:179], v[54:57]
	v_mfma_f32_16x16x32_bf16 v[50:53], v[168:171], v[176:179], v[50:53]
	v_mfma_f32_16x16x32_bf16 v[38:41], v[150:153], v[190:193], v[38:41]
	v_mfma_f32_16x16x32_bf16 v[34:37], v[168:171], v[190:193], v[34:37]
	v_mfma_f32_16x16x32_bf16 v[22:25], v[150:153], v[198:201], v[22:25]
	v_mfma_f32_16x16x32_bf16 v[18:21], v[168:171], v[198:201], v[18:21]
	v_mfma_f32_16x16x32_bf16 v[6:9], v[150:153], v[206:209], v[6:9]
	v_mfma_f32_16x16x32_bf16 v[2:5], v[168:171], v[206:209], v[2:5]
	s_barrier
	s_setprio 0
	s_add_i32 s51, s51, 2
	s_add_u32 s49, s49, 0x100
	s_addc_u32 s50, s50, 0
	s_cmp_gt_u32 s51, 41
	s_mov_b64 s[8:9], s[10:11]
	s_cbranch_scc0 .LBB0_504
	s_and_b64 vcc, exec, s[18:19]
	s_cbranch_vccz .LBB0_507
	s_barrier
